# GQA attention pass rewritten: Q fragments kept in registers (LDS reads halved), software-pipelined block-tiles, 3-slot LDS ring; shared min shift for the two q blocks
# speedup vs baseline: 1.0787x; 1.0402x over previous
; __device__ __forceinline__ float bf2f(unsigned short b) { return __uint_as_float((unsigned)b << 16); }
; __device__ __forceinline__ float sum_x32(float v) { auto rr = __builtin_amdgcn_permlane32_swap(__float_as_uint(v), __float_as_uint(v), false, false); return __uint_as_float(rr[0]) + __uint_as_float(rr[1]); }
; __device__ __forceinline__ void attn_pass_A2(const int tid, unsigned char* smem, const bf16_t* Q0w, int qpitch, const bf16_t* Kb, int kpitch, const bf16_t* Vb, int vpitch,
;                                              int b, int ntiles, float kmax, f32x16 (&o)[2][2], float (&linv)[2]) {
;     ...
;     const int lane = tid & 63, r32 = lane & 31, hi = lane >> 5;
;     float nshift[2], lsum[2] = {0.f, 0.f};
;     unsigned char* qs = smem + 2 * BUF + ((tid >> 6) * 64 + r32) * KP + hi * 16;
; #pragma unroll
;     for (int qb = 0; qb < 2; ++qb) {
;         const bf16_t* qp = Q0w + (size_t)(32 * qb + r32) * qpitch + 8 * hi; float ssq = 0.f;
; #pragma unroll
;         for (int ds = 0; ds < 4; ++ds) { const bf16x8 qv = *(const bf16x8*)(qp + 16 * ds); *(bf16x8*)(qs + qb * 32 * KP + ds * 32) = qv;
; #pragma unroll
;             for (int j = 0; j < 8; ++j) { const float f = bf2f((unsigned short)qv[j]); ssq += f * f; } }
;         nshift[qb] = -sqrtf(sum_x32(ssq)) * kmax;
; #pragma unroll
;         for (int d0 = 0; d0 < 2; ++d0)
; #pragma unroll
;             for (int r = 0; r < 16; ++r) o[qb][d0][r] = 0.f;
;     }
.LBB0_417:
	s_and_b64 vcc, exec, s[0:1]
	s_cbranch_vccz .LBB0_394
	s_and_b32 s0, s27, 0xffffffc0
	s_add_i32 s1, s0, 0xffffff00
	s_cmp_lt_i32 s0, s11
	s_cselect_b32 s0, s0, s1
	s_ashr_i32 s1, s0, 31
	s_add_u32 s0, s8, s0
	s_addc_u32 s1, s9, s1
	s_lshl_b64 s[0:1], s[0:1], 11
	v_readlane_b32 s2, v253, 22
	v_readlane_b32 s3, v253, 23
	s_add_u32 s2, s2, s0
	s_addc_u32 s3, s3, s1
	s_lshl_b32 s0, s26, 6
	s_ashr_i32 s1, s0, 31
	s_lshl_b64 s[12:13], s[0:1], 1
	s_add_u32 s0, s2, s12
	s_addc_u32 s1, s3, s13
	v_mov_b32_e32 v139, v193
	v_lshl_add_u64 v[0:1], s[0:1], 0, v[138:139]
	v_lshlrev_b32_e32 v192, 11, v218
	v_lshl_add_u64 v[0:1], v[0:1], 0, v[192:193]
	global_load_dwordx4 v[20:23], v[0:1], off
	global_load_dwordx4 v[24:27], v[0:1], off offset:32
	global_load_dwordx4 v[28:31], v[0:1], off offset:64
	global_load_dwordx4 v[32:35], v[0:1], off offset:96
	s_mov_b32 s0, 0x10000
	v_add_co_u32_e32 v10, vcc, s0, v0
	s_movk_i32 s0, 0x90
	s_nop 0
	v_addc_co_u32_e32 v11, vcc, 0, v1, vcc
	global_load_dwordx4 v[16:19], v[10:11], off
	v_and_b32_e32 v1, 0xfffffdf, v197
	v_mul_lo_u32 v1, v1, s0
	v_add_u32_e32 v1, 0, v1
	v_add_u32_e32 v139, v1, v138
	global_load_dwordx4 v[2:5], v[10:11], off offset:32
	global_load_dwordx4 v[6:9], v[10:11], off offset:64
	s_nop 0
	global_load_dwordx4 v[10:13], v[10:11], off offset:96
	s_lshl_b32 s0, s26, 4
	s_andn2_b32 s0, s0, 63
	s_ashr_i32 s1, s0, 31
	s_lshl_b64 s[0:1], s[0:1], 1
	v_readlane_b32 s2, v251, 33
	s_add_u32 s14, s2, s0
	v_readlane_b32 s2, v251, 34
	s_addc_u32 s15, s2, s1
	v_readlane_b32 s2, v251, 35
	s_add_u32 s16, s2, s0
	s_mov_b32 s2, 0xf800000
	v_readlane_b32 s0, v251, 36
	s_addc_u32 s17, s0, s1
	v_and_b32_e32 v192, 0x70, v217
	v_mov_b32_e32 v0, 0
	s_mov_b32 s3, 0
	v_lshl_add_u64 v[140:141], s[14:15], 0, v[192:193]
	v_lshl_add_u64 v[142:143], s[16:17], 0, v[192:193]
	v_mul_u32_u24_e32 v173, 0xc0, v215
	v_lshlrev_b32_e32 v174, 1, v216
	v_mov_b32_e32 v52, v0
	v_mov_b32_e32 v53, v0
	v_mov_b32_e32 v54, v0
	v_mov_b32_e32 v55, v0
	v_mov_b32_e32 v56, v0
	v_mov_b32_e32 v57, v0
	v_mov_b32_e32 v58, v0
	v_mov_b32_e32 v59, v0
	v_mov_b32_e32 v60, v0
	v_mov_b32_e32 v61, v0
	v_mov_b32_e32 v62, v0
	v_mov_b32_e32 v63, v0
	v_mov_b32_e32 v64, v0
	v_mov_b32_e32 v65, v0
	v_mov_b32_e32 v66, v0
	v_mov_b32_e32 v67, v0
	v_mov_b32_e32 v68, v0
	v_mov_b32_e32 v69, v0
	v_mov_b32_e32 v70, v0
	v_mov_b32_e32 v71, v0
	v_mov_b32_e32 v72, v0
	v_mov_b32_e32 v73, v0
	v_mov_b32_e32 v74, v0
	v_mov_b32_e32 v75, v0
	v_mov_b32_e32 v76, v0
	v_mov_b32_e32 v77, v0
	v_mov_b32_e32 v78, v0
	v_mov_b32_e32 v79, v0
	v_mov_b32_e32 v144, v0
	v_mov_b32_e32 v145, v0
	s_waitcnt vmcnt(7)
	v_and_b32_e32 v36, 0xffff0000, v20
	v_lshlrev_b32_e32 v1, 16, v20
	v_lshlrev_b32_e32 v37, 16, v21
	s_waitcnt vmcnt(4)
	ds_write_b128 v139, v[32:35] offset:43104
	v_and_b32_e32 v15, 0xffff0000, v34
	v_lshlrev_b32_e32 v14, 16, v34
	v_mul_f32_e32 v34, v36, v36
	v_fmac_f32_e32 v34, v1, v1
	v_and_b32_e32 v38, 0xffff0000, v21
	v_fmac_f32_e32 v34, v37, v37
	v_lshlrev_b32_e32 v39, 16, v22
	v_fmac_f32_e32 v34, v38, v38
	ds_write_b128 v139, v[20:23] offset:43008
	v_and_b32_e32 v22, 0xffff0000, v22
	v_fmac_f32_e32 v34, v39, v39
	v_lshlrev_b32_e32 v40, 16, v23
	v_fmac_f32_e32 v34, v22, v22
	v_and_b32_e32 v23, 0xffff0000, v23
	v_fmac_f32_e32 v34, v40, v40
	v_lshlrev_b32_e32 v41, 16, v24
	v_fmac_f32_e32 v34, v23, v23
	ds_write_b128 v139, v[24:27] offset:43040
	v_and_b32_e32 v24, 0xffff0000, v24
	v_fmac_f32_e32 v34, v41, v41
	v_lshlrev_b32_e32 v42, 16, v25
	v_fmac_f32_e32 v34, v24, v24
	v_and_b32_e32 v25, 0xffff0000, v25
	v_fmac_f32_e32 v34, v42, v42
	v_lshlrev_b32_e32 v43, 16, v26
	v_fmac_f32_e32 v34, v25, v25
	v_and_b32_e32 v26, 0xffff0000, v26
	v_fmac_f32_e32 v34, v43, v43
	v_lshlrev_b32_e32 v44, 16, v27
	v_fmac_f32_e32 v34, v26, v26
	v_and_b32_e32 v27, 0xffff0000, v27
	v_fmac_f32_e32 v34, v44, v44
	v_lshlrev_b32_e32 v45, 16, v28
	v_fmac_f32_e32 v34, v27, v27
	ds_write_b128 v139, v[28:31] offset:43072
	v_and_b32_e32 v28, 0xffff0000, v28
	v_fmac_f32_e32 v34, v45, v45
	v_lshlrev_b32_e32 v46, 16, v29
	v_fmac_f32_e32 v34, v28, v28
	v_and_b32_e32 v29, 0xffff0000, v29
	v_fmac_f32_e32 v34, v46, v46
	v_lshlrev_b32_e32 v47, 16, v30
	v_fmac_f32_e32 v34, v29, v29
	v_and_b32_e32 v30, 0xffff0000, v30
	v_fmac_f32_e32 v34, v47, v47
	v_lshlrev_b32_e32 v48, 16, v31
	v_fmac_f32_e32 v34, v30, v30
	v_and_b32_e32 v31, 0xffff0000, v31
	v_fmac_f32_e32 v34, v48, v48
	v_lshlrev_b32_e32 v49, 16, v32
	v_fmac_f32_e32 v34, v31, v31
	v_and_b32_e32 v32, 0xffff0000, v32
	v_fmac_f32_e32 v34, v49, v49
	v_lshlrev_b32_e32 v50, 16, v33
	v_fmac_f32_e32 v34, v32, v32
	v_and_b32_e32 v33, 0xffff0000, v33
	v_fmac_f32_e32 v34, v50, v50
	v_pk_mul_f32 v[14:15], v[14:15], v[14:15]
	v_fmac_f32_e32 v34, v33, v33
	v_and_b32_e32 v21, 0xffff0000, v35
	v_lshlrev_b32_e32 v20, 16, v35
	v_add_f32_e32 v14, v14, v34
	v_pk_mul_f32 v[20:21], v[20:21], v[20:21]
	v_add_f32_e32 v14, v15, v14
	v_add_f32_e32 v14, v20, v14
	v_add_f32_e32 v14, v21, v14
	v_mov_b32_e32 v15, v14
	s_nop 1
	v_permlane32_swap_b32_e32 v14, v15
	v_add_f32_e32 v14, v14, v15
	v_mul_f32_e32 v15, 0x4f800000, v14
	v_cmp_gt_f32_e32 vcc, s2, v14
	s_waitcnt vmcnt(3)
; __device__ __forceinline__ float bf2f(unsigned short b) { return __uint_as_float((unsigned)b << 16); }
; __device__ __forceinline__ float sum_x32(float v) { auto rr = __builtin_amdgcn_permlane32_swap(__float_as_uint(v), __float_as_uint(v), false, false); return __uint_as_float(rr[0]) + __uint_as_float(rr[1]); }
; __device__ __forceinline__ void attn_pass_A2(const int tid, unsigned char* smem, const bf16_t* Q0w, int qpitch, const bf16_t* Kb, int kpitch, const bf16_t* Vb, int vpitch,
;                                              int b, int ntiles, float kmax, f32x16 (&o)[2][2], float (&linv)[2]) {
;     ...
;         const bf16_t* qp = Q0w + (size_t)(32 * qb + r32) * qpitch + 8 * hi; float ssq = 0.f;
; #pragma unroll
;         for (int ds = 0; ds < 4; ++ds) { const bf16x8 qv = *(const bf16x8*)(qp + 16 * ds); *(bf16x8*)(qs + qb * 32 * KP + ds * 32) = qv;
; #pragma unroll
;             for (int j = 0; j < 8; ++j) { const float f = bf2f((unsigned short)qv[j]); ssq += f * f; } }
;         nshift[qb] = -sqrtf(sum_x32(ssq)) * kmax;
; #pragma unroll
;         for (int d0 = 0; d0 < 2; ++d0)
; #pragma unroll
;             for (int r = 0; r < 16; ++r) o[qb][d0][r] = 0.f;
;     }
;     const int krow = tid >> 3, kch = tid & 7;
;     u32x4 kreg, vreg;
;     auto gload = [&](int kt) {
;         const size_t rb = kt < 4 ? (size_t)(NLAT + 256 * b + 64 * kt) : (size_t)(SEQ * b + 64 * (kt - 4));
;         kreg = *(const u32x4*)(Kb + (rb + krow) * kpitch + 8 * kch); vreg = *(const u32x4*)(Vb + (rb + krow) * vpitch + 8 * kch);
;     };
;     auto lwrite = [&](int buf) { unsigned char* Ks = smem + buf * BUF; *(u32x4*)(Ks + krow * KP + 16 * kch) = kreg; *(u32x4*)(Ks + KBYTES + krow * VP + 16 * kch) = vreg; };
;     gload(0); lwrite(0); __syncthreads();
	ds_write_b128 v139, v[16:19] offset:47616
	v_lshlrev_b32_e32 v35, 16, v16
	v_cndmask_b32_e32 v14, v14, v15, vcc
	v_sqrt_f32_e32 v15, v14
	v_and_b32_e32 v16, 0xffff0000, v16
	v_mul_f32_e32 v1, v16, v16
	v_lshlrev_b32_e32 v36, 16, v17
	v_fmac_f32_e32 v1, v35, v35
	v_and_b32_e32 v17, 0xffff0000, v17
	v_fmac_f32_e32 v1, v36, v36
	v_add_u32_e32 v16, -1, v15
	v_fmac_f32_e32 v1, v17, v17
	v_add_u32_e32 v17, 1, v15
	v_fma_f32 v20, -v16, v15, v14
	v_fma_f32 v21, -v17, v15, v14
	v_cmp_ge_f32_e64 s[0:1], 0, v20
	v_lshlrev_b32_e32 v51, 16, v18
	v_fmac_f32_e32 v1, v51, v51
	v_cndmask_b32_e64 v15, v15, v16, s[0:1]
	v_cmp_lt_f32_e64 s[0:1], 0, v21
	v_mov_b32_e32 v32, v0
	v_mov_b32_e32 v33, v0
	v_cndmask_b32_e64 v15, v15, v17, s[0:1]
	v_mul_f32_e32 v16, 0x37800000, v15
	v_cndmask_b32_e32 v15, v15, v16, vcc
	v_cmp_class_f32_e32 vcc, v14, v227
	s_lshl_b32 s0, s10, 8
	s_add_i32 s0, s0, 0x8000
	v_cndmask_b32_e32 v14, v15, v14, vcc
	v_mul_f32_e64 v16, v214, -v14
	v_and_b32_e32 v14, 0xffff0000, v18
	v_fmac_f32_e32 v1, v14, v14
	v_lshlrev_b32_e32 v14, 16, v19
	s_ashr_i32 s1, s0, 31
	v_fmac_f32_e32 v1, v14, v14
	v_lshl_add_u64 v[14:15], s[0:1], 0, v[136:137]
	v_lshlrev_b64 v[14:15], 8, v[14:15]
	v_and_b32_e32 v17, 0xffff0000, v19
	v_lshl_add_u64 v[18:19], s[14:15], 0, v[14:15]
	v_lshl_add_u64 v[18:19], v[18:19], 0, v[192:193]
	v_lshl_add_u64 v[14:15], s[16:17], 0, v[14:15]
	global_load_dwordx4 v[128:131], v[18:19], off
	v_lshl_add_u64 v[14:15], v[14:15], 0, v[192:193]
	global_load_dwordx4 v[132:135], v[14:15], off
	v_fmac_f32_e32 v1, v17, v17
	s_waitcnt vmcnt(4)
	v_lshlrev_b32_e32 v14, 16, v2
	v_fmac_f32_e32 v1, v14, v14
	v_and_b32_e32 v14, 0xffff0000, v2
	v_fmac_f32_e32 v1, v14, v14
	v_lshlrev_b32_e32 v14, 16, v3
	v_fmac_f32_e32 v1, v14, v14
	v_and_b32_e32 v14, 0xffff0000, v3
	v_fmac_f32_e32 v1, v14, v14
	v_lshlrev_b32_e32 v14, 16, v4
	v_fmac_f32_e32 v1, v14, v14
	v_and_b32_e32 v14, 0xffff0000, v4
	v_fmac_f32_e32 v1, v14, v14
	v_lshlrev_b32_e32 v14, 16, v5
	v_fmac_f32_e32 v1, v14, v14
	v_and_b32_e32 v14, 0xffff0000, v5
	v_fmac_f32_e32 v1, v14, v14
	s_waitcnt vmcnt(3)
	v_lshlrev_b32_e32 v14, 16, v6
	v_fmac_f32_e32 v1, v14, v14
	v_and_b32_e32 v14, 0xffff0000, v6
	v_fmac_f32_e32 v1, v14, v14
	v_lshlrev_b32_e32 v14, 16, v7
	v_fmac_f32_e32 v1, v14, v14
	v_and_b32_e32 v14, 0xffff0000, v7
	v_fmac_f32_e32 v1, v14, v14
	v_lshlrev_b32_e32 v14, 16, v8
	v_fmac_f32_e32 v1, v14, v14
	v_and_b32_e32 v14, 0xffff0000, v8
	v_fmac_f32_e32 v1, v14, v14
	v_lshlrev_b32_e32 v14, 16, v9
	v_fmac_f32_e32 v1, v14, v14
	v_and_b32_e32 v14, 0xffff0000, v9
	v_fmac_f32_e32 v1, v14, v14
	s_waitcnt vmcnt(2)
	v_lshlrev_b32_e32 v14, 16, v10
	v_fmac_f32_e32 v1, v14, v14
	v_and_b32_e32 v14, 0xffff0000, v10
	v_fmac_f32_e32 v1, v14, v14
	v_lshlrev_b32_e32 v14, 16, v11
	v_fmac_f32_e32 v1, v14, v14
	v_and_b32_e32 v14, 0xffff0000, v11
	v_fmac_f32_e32 v1, v14, v14
	v_and_b32_e32 v15, 0xffff0000, v12
	v_lshlrev_b32_e32 v14, 16, v12
	v_pk_mul_f32 v[14:15], v[14:15], v[14:15]
	ds_write_b128 v139, v[2:5] offset:47648
	ds_write_b128 v139, v[6:9] offset:47680
	ds_write_b128 v139, v[10:13] offset:47712
	v_add_f32_e32 v1, v14, v1
	v_add_f32_e32 v1, v15, v1
	v_and_b32_e32 v15, 0xffff0000, v13
	v_lshlrev_b32_e32 v14, 16, v13
	v_pk_mul_f32 v[14:15], v[14:15], v[14:15]
	v_mov_b32_e32 v17, v16
	v_add_f32_e32 v1, v14, v1
	v_add_f32_e32 v1, v15, v1
	v_mov_b32_e32 v14, v1
	s_nop 1
	v_permlane32_swap_b32_e32 v1, v14
	v_add_f32_e32 v1, v1, v14
	v_mul_f32_e32 v14, 0x4f800000, v1
	v_cmp_gt_f32_e32 vcc, s2, v1
	v_mov_b32_e32 v18, v16
	v_mov_b32_e32 v19, v16
	v_cndmask_b32_e32 v1, v1, v14, vcc
	v_sqrt_f32_e32 v14, v1
	v_mov_b32_e32 v20, v16
	v_mov_b32_e32 v21, v16
	v_mov_b32_e32 v22, v16
	v_add_u32_e32 v2, -1, v14
	v_fma_f32 v3, -v2, v14, v1
	v_cmp_ge_f32_e64 s[0:1], 0, v3
	v_add_u32_e32 v3, 1, v14
	v_fma_f32 v4, -v3, v14, v1
	v_cndmask_b32_e64 v2, v14, v2, s[0:1]
	v_cmp_lt_f32_e64 s[0:1], 0, v4
	v_mov_b32_e32 v23, v16
	v_mov_b32_e32 v24, v16
	v_cndmask_b32_e64 v2, v2, v3, s[0:1]
	v_mul_f32_e32 v3, 0x37800000, v2
	v_cndmask_b32_e32 v2, v2, v3, vcc
	v_cmp_class_f32_e32 vcc, v1, v227
	s_movk_i32 s0, 0xc0
	v_mul_lo_u32 v172, v136, s0
	v_cndmask_b32_e32 v1, v2, v1, vcc
	v_add3_u32 v2, 0, v212, v192
	v_mul_f32_e64 v80, v214, -v1
	s_waitcnt vmcnt(1)
	ds_write_b128 v2, v[128:131]
	v_mad_u64_u32 v[2:3], s[0:1], v136, 48, v[2:3]
	s_waitcnt vmcnt(0)
	ds_write_b128 v2, v[132:135] offset:9216
	v_mov_b32_e32 v25, v16
	v_mov_b32_e32 v26, v16
	v_mov_b32_e32 v27, v16
	v_mov_b32_e32 v28, v16
	v_mov_b32_e32 v29, v16
	v_mov_b32_e32 v30, v16
	v_mov_b32_e32 v31, v16
	v_mov_b32_e32 v81, v80
	v_mov_b32_e32 v82, v80
	v_mov_b32_e32 v83, v80
	v_mov_b32_e32 v84, v80
	v_mov_b32_e32 v85, v80
	v_mov_b32_e32 v86, v80
	v_mov_b32_e32 v87, v80
	v_mov_b32_e32 v88, v80
	v_mov_b32_e32 v89, v80
	v_mov_b32_e32 v90, v80
	v_mov_b32_e32 v91, v80
	v_mov_b32_e32 v92, v80
	v_mov_b32_e32 v93, v80
	v_mov_b32_e32 v94, v80
	v_mov_b32_e32 v95, v80
	s_mov_b32 s2, 64
	v_mov_b32_e32 v1, v0
	v_mov_b32_e32 v2, v0
	v_mov_b32_e32 v3, v0
	v_mov_b32_e32 v4, v0
	v_mov_b32_e32 v5, v0
	v_mov_b32_e32 v6, v0
	v_mov_b32_e32 v7, v0
	v_mov_b32_e32 v8, v0
	v_mov_b32_e32 v9, v0
	v_mov_b32_e32 v10, v0
	v_mov_b32_e32 v11, v0
	v_mov_b32_e32 v12, v0
	v_mov_b32_e32 v13, v0
	v_mov_b32_e32 v14, v0
	v_mov_b32_e32 v15, v0
	v_mov_b32_e32 v34, v0
	v_mov_b32_e32 v35, v0
	v_mov_b32_e32 v36, v0
	v_mov_b32_e32 v37, v0
	v_mov_b32_e32 v38, v0
	v_mov_b32_e32 v39, v0
	v_mov_b32_e32 v40, v0
	v_mov_b32_e32 v41, v0
	v_mov_b32_e32 v42, v0
	v_mov_b32_e32 v43, v0
	v_mov_b32_e32 v44, v0
	v_mov_b32_e32 v45, v0
	v_mov_b32_e32 v46, v0
	v_mov_b32_e32 v47, v0
	v_mov_b32_e32 v48, v0
	v_mov_b32_e32 v49, v0
	v_mov_b32_e32 v50, v0
	v_mov_b32_e32 v51, v0
	s_waitcnt lgkmcnt(0)
	s_barrier
; __device__ __forceinline__ void attn_pass_A2(const int tid, unsigned char* smem, const bf16_t* Q0w, int qpitch, const bf16_t* Kb, int kpitch, const bf16_t* Vb, int vpitch,
;                                              int b, int ntiles, float kmax, f32x16 (&o)[2][2], float (&linv)[2]) {
;     ...
;     const int nhalf = (lane >> 4) & 1, q4 = (lane & 15) >> 2, p4 = lane & 3;
;     for (int kt = 0; kt < ntiles; ++kt) {
;         if (kt + 1 < ntiles) gload(kt + 1);
;         const unsigned char* Ks = smem + (kt & 1) * BUF; const unsigned char* Vs = Ks + KBYTES;
;         const unsigned char* kp = Ks + r32 * KP + hi * 16;
;         const unsigned char* vp = Vs + (4 * hi + q4) * VP + (16 * nhalf + 4 * p4) * 2;
; #pragma unroll
;         for (int kb = 0; kb < 2; ++kb) {
;             bf16x8 pf[2][2];
;             {
;                 f32x16 s0, s1;
; #pragma unroll
;                 for (int r = 0; r < 16; ++r) { s0[r] = nshift[0]; s1[r] = nshift[1]; }
; #pragma unroll
;                 for (int ds = 0; ds < 4; ++ds) {
;                     const bf16x8 kf = *(const bf16x8*)(kp + kb * 32 * KP + ds * 32);
;                     const bf16x8 q0 = *(const bf16x8*)(qs + ds * 32), q1 = *(const bf16x8*)(qs + 32 * KP + ds * 32);
;                     s0 = __builtin_amdgcn_mfma_f32_32x32x16_bf16(kf, q0, s0, 0, 0, 0);
;                     s1 = __builtin_amdgcn_mfma_f32_32x32x16_bf16(kf, q1, s1, 0, 0, 0);
;                 }
;                 float l0 = 0.f, l1 = 0.f;
; #pragma unroll
;                 for (int r = 0; r < 16; ++r) { s0[r] = __builtin_amdgcn_exp2f(s0[r]); l0 += s0[r]; }
; #pragma unroll
;                 for (int r = 0; r < 16; ++r) { s1[r] = __builtin_amdgcn_exp2f(s1[r]); l1 += s1[r]; }
;                 lsum[0] += l0; lsum[1] += l1;
; #pragma unroll
;                 for (int j = 0; j < 2; ++j) {
;                     u32x4 w0, w1;
;                     w0.x = cvt_pk_bf16(s0[8 * j + 0], s0[8 * j + 1]); w0.y = cvt_pk_bf16(s0[8 * j + 2], s0[8 * j + 3]); w0.z = cvt_pk_bf16(s0[8 * j + 4], s0[8 * j + 5]); w0.w = cvt_pk_bf16(s0[8 * j + 6], s0[8 * j + 7]);
;                     w1.x = cvt_pk_bf16(s1[8 * j + 0], s1[8 * j + 1]); w1.y = cvt_pk_bf16(s1[8 * j + 2], s1[8 * j + 3]); w1.z = cvt_pk_bf16(s1[8 * j + 4], s1[8 * j + 5]); w1.w = cvt_pk_bf16(s1[8 * j + 6], s1[8 * j + 7]);
	v_min_f32_e32 v16, v16, v80
	v_mov_b32_e32 v17, v16
	v_mov_b32_e32 v18, v16
	v_mov_b32_e32 v19, v16
	v_mov_b32_e32 v20, v16
	v_mov_b32_e32 v21, v16
	v_mov_b32_e32 v22, v16
	v_mov_b32_e32 v23, v16
	v_mov_b32_e32 v24, v16
	v_mov_b32_e32 v25, v16
	v_mov_b32_e32 v26, v16
	v_mov_b32_e32 v27, v16
	v_mov_b32_e32 v28, v16
	v_mov_b32_e32 v29, v16
	v_mov_b32_e32 v30, v16
	v_mov_b32_e32 v31, v16
	ds_read_b128 v[146:149], v139 offset:43008
	ds_read_b128 v[150:153], v139 offset:43040
	ds_read_b128 v[154:157], v139 offset:43072
	ds_read_b128 v[158:161], v139 offset:43104
	ds_read_b128 v[176:179], v139 offset:47616
	ds_read_b128 v[180:183], v139 offset:47648
	ds_read_b128 v[184:187], v139 offset:47680
	ds_read_b128 v[188:191], v139 offset:47712
	s_mov_b64 s[66:67], s[14:15]
	s_mov_b64 s[68:69], s[16:17]
	s_lshl_b32 s2, s10, 8
	s_add_i32 s65, s2, 0x8000
	s_lshl_b32 s2, s10, 13
	s_add_i32 s32, s2, 0xffffff00
	v_lshl_add_u32 v236, v136, 8, v192
	s_mov_b32 s56, 0
	s_movk_i32 s57, 0x5400
	s_mov_b32 s58, 0xa800
	s_mov_b32 s59, 0
	s_add_i32 s71, s25, -1
	s_add_i32 s70, s59, 1
	s_min_u32 s70, s70, s71
	s_cmp_lt_u32 s70, 4
	s_cselect_b32 s2, s65, s32
	s_lshl_b32 s3, s70, 6
	s_add_i32 s2, s2, s3
	s_lshl_b32 s2, s2, 8
	s_add_u32 s60, s66, s2
	s_addc_u32 s61, s67, 0
	s_add_u32 s62, s68, s2
	s_addc_u32 s63, s69, 0
	global_load_dwordx4 v[132:135], v236, s[60:61]
	global_load_dwordx4 v[230:233], v236, s[62:63]
	v_add3_u32 v234, s57, v212, v192
	v_add3_u32 v235, s57, v172, v192
	s_waitcnt vmcnt(0)
	ds_write_b128 v234, v[132:135]
	ds_write_b128 v235, v[230:233] offset:9216
	s_waitcnt lgkmcnt(0)
	s_barrier
	s_add_i32 s71, s25, -1
	s_add_i32 s70, s59, 2
	s_min_u32 s70, s70, s71
	s_cmp_lt_u32 s70, 4
	s_cselect_b32 s2, s65, s32
	s_lshl_b32 s3, s70, 6
	s_add_i32 s2, s2, s3
	s_lshl_b32 s2, s2, 8
	s_add_u32 s60, s66, s2
	s_addc_u32 s61, s67, 0
	s_add_u32 s62, s68, s2
	s_addc_u32 s63, s69, 0
	global_load_dwordx4 v[132:135], v236, s[60:61]
	global_load_dwordx4 v[230:233], v236, s[62:63]
	v_add3_u32 v170, s57, v213, v138
	v_add3_u32 v171, s56, v173, v174
	v_add3_u32 v210, s57, v173, v174
	v_add3_u32 v234, s56, v213, v138
	ds_read_b128 v[198:201], v234 offset:0
	ds_read_b128 v[202:205], v234 offset:32
	ds_read_b128 v[206:209], v234 offset:64
	ds_read_b128 v[128:131], v234 offset:96
	s_waitcnt lgkmcnt(3)
	v_mfma_f32_32x32x16_bf16 v[80:95], v[198:201], v[146:149], v[16:31]
	s_waitcnt lgkmcnt(2)
	v_mfma_f32_32x32x16_bf16 v[80:95], v[202:205], v[150:153], v[80:95]
	s_waitcnt lgkmcnt(1)
	v_mfma_f32_32x32x16_bf16 v[80:95], v[206:209], v[154:157], v[80:95]
	s_waitcnt lgkmcnt(0)
	v_mfma_f32_32x32x16_bf16 v[80:95], v[128:131], v[158:161], v[80:95]
	s_nop 7
	s_nop 3
	v_mfma_f32_32x32x16_bf16 v[96:111], v[198:201], v[176:179], v[16:31]
	ds_read_b128 v[198:201], v234 offset:4608
	v_exp_f32_e32 v80, v80
	v_exp_f32_e32 v81, v81
	v_exp_f32_e32 v82, v82
	v_add_f32_e32 v144, v144, v80
	v_exp_f32_e32 v83, v83
	v_add_f32_e32 v144, v144, v81
	v_cvt_pk_bf16_f32 v112, v80, v81
	v_exp_f32_e32 v84, v84
	v_add_f32_e32 v144, v144, v82
	v_exp_f32_e32 v85, v85
	v_add_f32_e32 v144, v144, v83
	v_cvt_pk_bf16_f32 v113, v82, v83
	v_exp_f32_e32 v86, v86
	v_mfma_f32_32x32x16_bf16 v[96:111], v[202:205], v[180:183], v[96:111]
	ds_read_b128 v[202:205], v234 offset:4640
	v_add_f32_e32 v144, v144, v84
	v_exp_f32_e32 v87, v87
	v_add_f32_e32 v144, v144, v85
	v_cvt_pk_bf16_f32 v114, v84, v85
	v_exp_f32_e32 v88, v88
	v_add_f32_e32 v144, v144, v86
	v_exp_f32_e32 v89, v89
	v_add_f32_e32 v144, v144, v87
	v_cvt_pk_bf16_f32 v115, v86, v87
	v_exp_f32_e32 v90, v90
	v_add_f32_e32 v144, v144, v88
	v_exp_f32_e32 v91, v91
	v_add_f32_e32 v144, v144, v89
	v_mfma_f32_32x32x16_bf16 v[96:111], v[206:209], v[184:187], v[96:111]
	ds_read_b128 v[206:209], v234 offset:4672
	v_cvt_pk_bf16_f32 v116, v88, v89
	v_exp_f32_e32 v92, v92
	v_add_f32_e32 v144, v144, v90
	v_exp_f32_e32 v93, v93
	v_add_f32_e32 v144, v144, v91
	v_cvt_pk_bf16_f32 v117, v90, v91
	v_exp_f32_e32 v94, v94
	v_add_f32_e32 v144, v144, v92
	v_exp_f32_e32 v95, v95
	v_add_f32_e32 v144, v144, v93
	v_cvt_pk_bf16_f32 v118, v92, v93
	v_add_f32_e32 v144, v144, v94
	v_add_f32_e32 v144, v144, v95
	v_cvt_pk_bf16_f32 v119, v94, v95
	v_mfma_f32_32x32x16_bf16 v[96:111], v[128:131], v[188:191], v[96:111]
	ds_read_b128 v[128:131], v234 offset:4704
	ds_read_b64_tr_b16 v[162:163], v171 offset:9216
	ds_read_b64_tr_b16 v[164:165], v171 offset:10752
	ds_read_b64_tr_b16 v[166:167], v171 offset:9280
	ds_read_b64_tr_b16 v[168:169], v171 offset:10816
	ds_read_b64_tr_b16 v[214:215], v171 offset:12288
	ds_read_b64_tr_b16 v[216:217], v171 offset:13824
	ds_read_b64_tr_b16 v[218:219], v171 offset:12352
	ds_read_b64_tr_b16 v[220:221], v171 offset:13888
	s_waitcnt lgkmcnt(8)
	s_nop 3
; __device__ __forceinline__ void attn_pass_A2(const int tid, unsigned char* smem, const bf16_t* Q0w, int qpitch, const bf16_t* Kb, int kpitch, const bf16_t* Vb, int vpitch,
;                                              int b, int ntiles, float kmax, f32x16 (&o)[2][2], float (&linv)[2]) {
;     ...
;     for (int kt = 0; kt < ntiles; ++kt) {
;         if (kt + 1 < ntiles) gload(kt + 1);
;         const unsigned char* Ks = smem + (kt & 1) * BUF; const unsigned char* Vs = Ks + KBYTES;
;         const unsigned char* kp = Ks + r32 * KP + hi * 16;
;         const unsigned char* vp = Vs + (4 * hi + q4) * VP + (16 * nhalf + 4 * p4) * 2;
; #pragma unroll
;         for (int kb = 0; kb < 2; ++kb) {
;             bf16x8 pf[2][2];
;             {
;                 f32x16 s0, s1;
; #pragma unroll
;                 for (int r = 0; r < 16; ++r) { s0[r] = nshift[0]; s1[r] = nshift[1]; }
; #pragma unroll
;                 for (int ds = 0; ds < 4; ++ds) {
;                     const bf16x8 kf = *(const bf16x8*)(kp + kb * 32 * KP + ds * 32);
;                     const bf16x8 q0 = *(const bf16x8*)(qs + ds * 32), q1 = *(const bf16x8*)(qs + 32 * KP + ds * 32);
;                     s0 = __builtin_amdgcn_mfma_f32_32x32x16_bf16(kf, q0, s0, 0, 0, 0);
;                     s1 = __builtin_amdgcn_mfma_f32_32x32x16_bf16(kf, q1, s1, 0, 0, 0);
;                 }
;                 float l0 = 0.f, l1 = 0.f;
; #pragma unroll
;                 for (int r = 0; r < 16; ++r) { s0[r] = __builtin_amdgcn_exp2f(s0[r]); l0 += s0[r]; }
; #pragma unroll
;                 for (int r = 0; r < 16; ++r) { s1[r] = __builtin_amdgcn_exp2f(s1[r]); l1 += s1[r]; }
;                 lsum[0] += l0; lsum[1] += l1;
; #pragma unroll
;                 for (int j = 0; j < 2; ++j) {
;                     u32x4 w0, w1;
;                     w0.x = cvt_pk_bf16(s0[8 * j + 0], s0[8 * j + 1]); w0.y = cvt_pk_bf16(s0[8 * j + 2], s0[8 * j + 3]); w0.z = cvt_pk_bf16(s0[8 * j + 4], s0[8 * j + 5]); w0.w = cvt_pk_bf16(s0[8 * j + 6], s0[8 * j + 7]);
;                     w1.x = cvt_pk_bf16(s1[8 * j + 0], s1[8 * j + 1]); w1.y = cvt_pk_bf16(s1[8 * j + 2], s1[8 * j + 3]); w1.z = cvt_pk_bf16(s1[8 * j + 4], s1[8 * j + 5]); w1.w = cvt_pk_bf16(s1[8 * j + 6], s1[8 * j + 7]);
;                     pf[0][j] = __builtin_bit_cast(bf16x8, w0); pf[1][j] = __builtin_bit_cast(bf16x8, w1);
;                 }
;             }
.Laattn_loop:
	v_mfma_f32_32x32x16_bf16 v[80:95], v[198:201], v[146:149], v[16:31]
	v_exp_f32_e32 v96, v96
	v_exp_f32_e32 v97, v97
	v_exp_f32_e32 v98, v98
	v_add_f32_e32 v145, v145, v96
	v_exp_f32_e32 v99, v99
	v_mfma_f32_32x32x16_bf16 v[80:95], v[202:205], v[150:153], v[80:95]
	v_add3_u32 v234, s58, v212, v192
	v_add3_u32 v235, s58, v172, v192
	v_add_f32_e32 v145, v145, v97
	v_cvt_pk_bf16_f32 v120, v96, v97
	v_exp_f32_e32 v100, v100
	v_add_f32_e32 v145, v145, v98
	v_exp_f32_e32 v101, v101
	v_mfma_f32_32x32x16_bf16 v[80:95], v[206:209], v[154:157], v[80:95]
	v_add_f32_e32 v145, v145, v99
	v_cvt_pk_bf16_f32 v121, v98, v99
	v_exp_f32_e32 v102, v102
	v_add_f32_e32 v145, v145, v100
	v_exp_f32_e32 v103, v103
	v_add_f32_e32 v145, v145, v101
	v_mfma_f32_32x32x16_bf16 v[80:95], v[128:131], v[158:161], v[80:95]
	v_cvt_pk_bf16_f32 v122, v100, v101
	v_exp_f32_e32 v104, v104
	v_add_f32_e32 v145, v145, v102
	v_exp_f32_e32 v105, v105
	v_add_f32_e32 v145, v145, v103
	v_cvt_pk_bf16_f32 v123, v102, v103
	s_waitcnt lgkmcnt(6)
	v_mfma_f32_32x32x16_bf16 v[64:79], v[162:165], v[112:115], v[64:79]
	s_waitcnt vmcnt(0)
	ds_write_b128 v234, v[132:135]
	v_exp_f32_e32 v106, v106
	v_add_f32_e32 v145, v145, v104
	v_exp_f32_e32 v107, v107
	v_add_f32_e32 v145, v145, v105
	v_cvt_pk_bf16_f32 v124, v104, v105
	v_exp_f32_e32 v108, v108
	s_waitcnt lgkmcnt(5)
	v_mfma_f32_32x32x16_bf16 v[48:63], v[166:169], v[112:115], v[48:63]
	v_add_f32_e32 v145, v145, v106
	v_exp_f32_e32 v109, v109
	v_add_f32_e32 v145, v145, v107
	v_cvt_pk_bf16_f32 v125, v106, v107
	v_exp_f32_e32 v110, v110
	s_waitcnt lgkmcnt(3)
	v_mfma_f32_32x32x16_bf16 v[64:79], v[214:217], v[116:119], v[64:79]
	ds_write_b128 v235, v[230:233] offset:9216
	v_add_f32_e32 v145, v145, v108
	v_exp_f32_e32 v111, v111
	v_add_f32_e32 v145, v145, v109
	v_cvt_pk_bf16_f32 v126, v108, v109
	v_add_f32_e32 v145, v145, v110
	v_add_f32_e32 v145, v145, v111
	v_cvt_pk_bf16_f32 v127, v110, v111
	s_waitcnt lgkmcnt(2)
	v_mfma_f32_32x32x16_bf16 v[48:63], v[218:221], v[116:119], v[48:63]
	v_mfma_f32_32x32x16_bf16 v[96:111], v[198:201], v[176:179], v[16:31]
	ds_read_b128 v[198:201], v170 offset:0
	v_exp_f32_e32 v80, v80
	v_exp_f32_e32 v81, v81
	v_exp_f32_e32 v82, v82
	v_add_f32_e32 v144, v144, v80
	v_exp_f32_e32 v83, v83
	v_mfma_f32_32x32x16_bf16 v[96:111], v[202:205], v[180:183], v[96:111]
	ds_read_b128 v[202:205], v170 offset:32
	s_add_i32 s71, s25, -1
	s_add_i32 s70, s59, 3
	s_min_u32 s70, s70, s71
	s_cmp_lt_u32 s70, 4
	s_cselect_b32 s2, s65, s32
	s_lshl_b32 s3, s70, 6
	s_add_i32 s2, s2, s3
	s_lshl_b32 s2, s2, 8
	s_add_u32 s60, s66, s2
	s_addc_u32 s61, s67, 0
	s_add_u32 s62, s68, s2
	s_addc_u32 s63, s69, 0
	v_add_f32_e32 v144, v144, v81
	v_cvt_pk_bf16_f32 v112, v80, v81
	v_exp_f32_e32 v84, v84
	v_add_f32_e32 v144, v144, v82
	v_exp_f32_e32 v85, v85
	v_mfma_f32_32x32x16_bf16 v[96:111], v[206:209], v[184:187], v[96:111]
	ds_read_b128 v[206:209], v170 offset:64
	v_add_f32_e32 v144, v144, v83
	v_cvt_pk_bf16_f32 v113, v82, v83
	v_exp_f32_e32 v86, v86
	v_add_f32_e32 v144, v144, v84
	v_exp_f32_e32 v87, v87
	v_add_f32_e32 v144, v144, v85
	v_mfma_f32_32x32x16_bf16 v[96:111], v[128:131], v[188:191], v[96:111]
	ds_read_b128 v[128:131], v170 offset:96
	global_load_dwordx4 v[132:135], v236, s[60:61]
	global_load_dwordx4 v[230:233], v236, s[62:63]
	v_cvt_pk_bf16_f32 v114, v84, v85
	v_exp_f32_e32 v88, v88
	v_add_f32_e32 v144, v144, v86
	v_exp_f32_e32 v89, v89
	v_add_f32_e32 v144, v144, v87
	v_cvt_pk_bf16_f32 v115, v86, v87
	v_mfma_f32_32x32x16_bf16 v[32:47], v[162:165], v[120:123], v[32:47]
	ds_read_b64_tr_b16 v[162:163], v171 offset:15360
	ds_read_b64_tr_b16 v[164:165], v171 offset:16896
	v_exp_f32_e32 v90, v90
	v_add_f32_e32 v144, v144, v88
	v_exp_f32_e32 v91, v91
	v_add_f32_e32 v144, v144, v89
	v_cvt_pk_bf16_f32 v116, v88, v89
	v_exp_f32_e32 v92, v92
	v_mfma_f32_32x32x16_bf16 v[0:15], v[166:169], v[120:123], v[0:15]
	ds_read_b64_tr_b16 v[166:167], v171 offset:15424
	ds_read_b64_tr_b16 v[168:169], v171 offset:16960
	v_add_f32_e32 v144, v144, v90
	v_exp_f32_e32 v93, v93
	v_add_f32_e32 v144, v144, v91
	v_cvt_pk_bf16_f32 v117, v90, v91
	v_exp_f32_e32 v94, v94
	v_mfma_f32_32x32x16_bf16 v[32:47], v[214:217], v[124:127], v[32:47]
	ds_read_b64_tr_b16 v[214:215], v171 offset:18432
	ds_read_b64_tr_b16 v[216:217], v171 offset:19968
	v_add_f32_e32 v144, v144, v92
	v_exp_f32_e32 v95, v95
	v_add_f32_e32 v144, v144, v93
	v_cvt_pk_bf16_f32 v118, v92, v93
	v_add_f32_e32 v144, v144, v94
	v_add_f32_e32 v144, v144, v95
	v_cvt_pk_bf16_f32 v119, v94, v95
	v_mfma_f32_32x32x16_bf16 v[0:15], v[218:221], v[124:127], v[0:15]
	ds_read_b64_tr_b16 v[218:219], v171 offset:18496
	ds_read_b64_tr_b16 v[220:221], v171 offset:20032
	s_waitcnt lgkmcnt(11)
	v_mfma_f32_32x32x16_bf16 v[80:95], v[198:201], v[146:149], v[16:31]
	v_exp_f32_e32 v96, v96
	v_exp_f32_e32 v97, v97
	v_exp_f32_e32 v98, v98
	v_add_f32_e32 v145, v145, v96
	v_exp_f32_e32 v99, v99
	s_waitcnt lgkmcnt(10)
	v_mfma_f32_32x32x16_bf16 v[80:95], v[202:205], v[150:153], v[80:95]
	v_add_f32_e32 v145, v145, v97
	v_cvt_pk_bf16_f32 v120, v96, v97
	v_exp_f32_e32 v100, v100
	v_add_f32_e32 v145, v145, v98
	v_exp_f32_e32 v101, v101
	s_waitcnt lgkmcnt(9)
	v_mfma_f32_32x32x16_bf16 v[80:95], v[206:209], v[154:157], v[80:95]
	v_add_f32_e32 v145, v145, v99
	v_cvt_pk_bf16_f32 v121, v98, v99
	v_exp_f32_e32 v102, v102
	v_add_f32_e32 v145, v145, v100
	v_exp_f32_e32 v103, v103
	v_add_f32_e32 v145, v145, v101
	s_waitcnt lgkmcnt(8)
	v_mfma_f32_32x32x16_bf16 v[80:95], v[128:131], v[158:161], v[80:95]
	v_cvt_pk_bf16_f32 v122, v100, v101
	v_exp_f32_e32 v104, v104
	v_add_f32_e32 v145, v145, v102
	v_exp_f32_e32 v105, v105
	v_add_f32_e32 v145, v145, v103
	v_cvt_pk_bf16_f32 v123, v102, v103
	s_waitcnt lgkmcnt(6)
; __device__ __forceinline__ void attn_pass_A2(const int tid, unsigned char* smem, const bf16_t* Q0w, int qpitch, const bf16_t* Kb, int kpitch, const bf16_t* Vb, int vpitch,
;                                              int b, int ntiles, float kmax, f32x16 (&o)[2][2], float (&linv)[2]) {
;     ...
;     for (int kt = 0; kt < ntiles; ++kt) {
;         if (kt + 1 < ntiles) gload(kt + 1);
;         const unsigned char* Ks = smem + (kt & 1) * BUF; const unsigned char* Vs = Ks + KBYTES;
;         const unsigned char* kp = Ks + r32 * KP + hi * 16;
;         const unsigned char* vp = Vs + (4 * hi + q4) * VP + (16 * nhalf + 4 * p4) * 2;
; #pragma unroll
;         for (int kb = 0; kb < 2; ++kb) {
;             bf16x8 pf[2][2];
;             {
;                 f32x16 s0, s1;
; #pragma unroll
;                 for (int r = 0; r < 16; ++r) { s0[r] = nshift[0]; s1[r] = nshift[1]; }
; #pragma unroll
;                 for (int ds = 0; ds < 4; ++ds) {
;                     const bf16x8 kf = *(const bf16x8*)(kp + kb * 32 * KP + ds * 32);
;                     const bf16x8 q0 = *(const bf16x8*)(qs + ds * 32), q1 = *(const bf16x8*)(qs + 32 * KP + ds * 32);
;                     s0 = __builtin_amdgcn_mfma_f32_32x32x16_bf16(kf, q0, s0, 0, 0, 0);
;                     s1 = __builtin_amdgcn_mfma_f32_32x32x16_bf16(kf, q1, s1, 0, 0, 0);
;                 }
;                 float l0 = 0.f, l1 = 0.f;
; #pragma unroll
;                 for (int r = 0; r < 16; ++r) { s0[r] = __builtin_amdgcn_exp2f(s0[r]); l0 += s0[r]; }
; #pragma unroll
;                 for (int r = 0; r < 16; ++r) { s1[r] = __builtin_amdgcn_exp2f(s1[r]); l1 += s1[r]; }
;                 lsum[0] += l0; lsum[1] += l1;
; #pragma unroll
;                 for (int j = 0; j < 2; ++j) {
;                     u32x4 w0, w1;
;                     w0.x = cvt_pk_bf16(s0[8 * j + 0], s0[8 * j + 1]); w0.y = cvt_pk_bf16(s0[8 * j + 2], s0[8 * j + 3]); w0.z = cvt_pk_bf16(s0[8 * j + 4], s0[8 * j + 5]); w0.w = cvt_pk_bf16(s0[8 * j + 6], s0[8 * j + 7]);
;                     w1.x = cvt_pk_bf16(s1[8 * j + 0], s1[8 * j + 1]); w1.y = cvt_pk_bf16(s1[8 * j + 2], s1[8 * j + 3]); w1.z = cvt_pk_bf16(s1[8 * j + 4], s1[8 * j + 5]); w1.w = cvt_pk_bf16(s1[8 * j + 6], s1[8 * j + 7]);
;                     pf[0][j] = __builtin_bit_cast(bf16x8, w0); pf[1][j] = __builtin_bit_cast(bf16x8, w1);
;                 }
;             }
	v_mfma_f32_32x32x16_bf16 v[64:79], v[162:165], v[112:115], v[64:79]
	v_exp_f32_e32 v106, v106
	v_add_f32_e32 v145, v145, v104
	v_exp_f32_e32 v107, v107
	v_add_f32_e32 v145, v145, v105
	v_cvt_pk_bf16_f32 v124, v104, v105
	v_exp_f32_e32 v108, v108
	s_waitcnt lgkmcnt(4)
	v_mfma_f32_32x32x16_bf16 v[48:63], v[166:169], v[112:115], v[48:63]
	v_add_f32_e32 v145, v145, v106
	v_exp_f32_e32 v109, v109
	v_add_f32_e32 v145, v145, v107
	v_cvt_pk_bf16_f32 v125, v106, v107
	v_exp_f32_e32 v110, v110
	s_waitcnt lgkmcnt(2)
	v_mfma_f32_32x32x16_bf16 v[64:79], v[214:217], v[116:119], v[64:79]
	v_add_f32_e32 v145, v145, v108
	v_exp_f32_e32 v111, v111
	v_add_f32_e32 v145, v145, v109
	v_cvt_pk_bf16_f32 v126, v108, v109
	v_add_f32_e32 v145, v145, v110
	v_add_f32_e32 v145, v145, v111
	v_cvt_pk_bf16_f32 v127, v110, v111
	s_waitcnt lgkmcnt(0)
	v_mfma_f32_32x32x16_bf16 v[48:63], v[218:221], v[116:119], v[48:63]
	v_mfma_f32_32x32x16_bf16 v[96:111], v[198:201], v[176:179], v[16:31]
	ds_read_b128 v[198:201], v170 offset:4608
	v_exp_f32_e32 v80, v80
	v_exp_f32_e32 v81, v81
	v_exp_f32_e32 v82, v82
	v_add_f32_e32 v144, v144, v80
	v_exp_f32_e32 v83, v83
	v_mfma_f32_32x32x16_bf16 v[96:111], v[202:205], v[180:183], v[96:111]
	ds_read_b128 v[202:205], v170 offset:4640
	v_add3_u32 v222, s58, v213, v138
	v_add3_u32 v223, s57, v173, v174
	v_add3_u32 v224, s58, v173, v174
	v_add_f32_e32 v144, v144, v81
	v_cvt_pk_bf16_f32 v112, v80, v81
	v_exp_f32_e32 v84, v84
	v_add_f32_e32 v144, v144, v82
	v_exp_f32_e32 v85, v85
	v_mfma_f32_32x32x16_bf16 v[96:111], v[206:209], v[184:187], v[96:111]
	ds_read_b128 v[206:209], v170 offset:4672
	v_add_f32_e32 v144, v144, v83
	v_cvt_pk_bf16_f32 v113, v82, v83
	v_exp_f32_e32 v86, v86
	v_add_f32_e32 v144, v144, v84
	v_exp_f32_e32 v87, v87
	v_add_f32_e32 v144, v144, v85
	v_mfma_f32_32x32x16_bf16 v[96:111], v[128:131], v[188:191], v[96:111]
	ds_read_b128 v[128:131], v170 offset:4704
	v_cvt_pk_bf16_f32 v114, v84, v85
	v_exp_f32_e32 v88, v88
	v_add_f32_e32 v144, v144, v86
	v_exp_f32_e32 v89, v89
	v_add_f32_e32 v144, v144, v87
	v_cvt_pk_bf16_f32 v115, v86, v87
	v_mfma_f32_32x32x16_bf16 v[32:47], v[162:165], v[120:123], v[32:47]
	ds_read_b64_tr_b16 v[162:163], v210 offset:9216
	ds_read_b64_tr_b16 v[164:165], v210 offset:10752
	v_exp_f32_e32 v90, v90
	v_add_f32_e32 v144, v144, v88
	v_exp_f32_e32 v91, v91
	v_add_f32_e32 v144, v144, v89
	v_cvt_pk_bf16_f32 v116, v88, v89
	v_exp_f32_e32 v92, v92
	v_mfma_f32_32x32x16_bf16 v[0:15], v[166:169], v[120:123], v[0:15]
	ds_read_b64_tr_b16 v[166:167], v210 offset:9280
	ds_read_b64_tr_b16 v[168:169], v210 offset:10816
	s_mov_b32 s2, s56
	s_mov_b32 s56, s57
	s_mov_b32 s57, s58
	s_mov_b32 s58, s2
	s_add_i32 s59, s59, 1
	v_add_f32_e32 v144, v144, v90
	v_exp_f32_e32 v93, v93
	v_add_f32_e32 v144, v144, v91
	v_cvt_pk_bf16_f32 v117, v90, v91
	v_exp_f32_e32 v94, v94
	v_mfma_f32_32x32x16_bf16 v[32:47], v[214:217], v[124:127], v[32:47]
	ds_read_b64_tr_b16 v[214:215], v210 offset:12288
	ds_read_b64_tr_b16 v[216:217], v210 offset:13824
	v_add_f32_e32 v144, v144, v92
	v_exp_f32_e32 v95, v95
	v_add_f32_e32 v144, v144, v93
	v_cvt_pk_bf16_f32 v118, v92, v93
	v_add_f32_e32 v144, v144, v94
	v_add_f32_e32 v144, v144, v95
	v_cvt_pk_bf16_f32 v119, v94, v95
	v_mfma_f32_32x32x16_bf16 v[0:15], v[218:221], v[124:127], v[0:15]
	ds_read_b64_tr_b16 v[218:219], v210 offset:12352
	ds_read_b64_tr_b16 v[220:221], v210 offset:13888
	s_waitcnt lgkmcnt(8)
	s_barrier
	v_mfma_f32_32x32x16_bf16 v[80:95], v[198:201], v[146:149], v[16:31]
	v_exp_f32_e32 v96, v96
	v_exp_f32_e32 v97, v97
	v_exp_f32_e32 v98, v98
	v_add_f32_e32 v145, v145, v96
	v_exp_f32_e32 v99, v99
	v_mfma_f32_32x32x16_bf16 v[80:95], v[202:205], v[150:153], v[80:95]
	v_add3_u32 v234, s58, v212, v192
	v_add3_u32 v235, s58, v172, v192
	v_add_f32_e32 v145, v145, v97
	v_cvt_pk_bf16_f32 v120, v96, v97
	v_exp_f32_e32 v100, v100
	v_add_f32_e32 v145, v145, v98
	v_exp_f32_e32 v101, v101
	v_mfma_f32_32x32x16_bf16 v[80:95], v[206:209], v[154:157], v[80:95]
	v_add_f32_e32 v145, v145, v99
	v_cvt_pk_bf16_f32 v121, v98, v99
	v_exp_f32_e32 v102, v102
	v_add_f32_e32 v145, v145, v100
	v_exp_f32_e32 v103, v103
	v_add_f32_e32 v145, v145, v101
	v_mfma_f32_32x32x16_bf16 v[80:95], v[128:131], v[158:161], v[80:95]
	v_cvt_pk_bf16_f32 v122, v100, v101
	v_exp_f32_e32 v104, v104
	v_add_f32_e32 v145, v145, v102
	v_exp_f32_e32 v105, v105
	v_add_f32_e32 v145, v145, v103
	v_cvt_pk_bf16_f32 v123, v102, v103
	s_waitcnt lgkmcnt(6)
	v_mfma_f32_32x32x16_bf16 v[64:79], v[162:165], v[112:115], v[64:79]
	s_waitcnt vmcnt(0)
	ds_write_b128 v234, v[132:135]
	v_exp_f32_e32 v106, v106
	v_add_f32_e32 v145, v145, v104
	v_exp_f32_e32 v107, v107
	v_add_f32_e32 v145, v145, v105
	v_cvt_pk_bf16_f32 v124, v104, v105
	v_exp_f32_e32 v108, v108
	s_waitcnt lgkmcnt(5)
	v_mfma_f32_32x32x16_bf16 v[48:63], v[166:169], v[112:115], v[48:63]
	v_add_f32_e32 v145, v145, v106
	v_exp_f32_e32 v109, v109
	v_add_f32_e32 v145, v145, v107
	v_cvt_pk_bf16_f32 v125, v106, v107
	v_exp_f32_e32 v110, v110
	s_waitcnt lgkmcnt(3)
	v_mfma_f32_32x32x16_bf16 v[64:79], v[214:217], v[116:119], v[64:79]
	ds_write_b128 v235, v[230:233] offset:9216
	v_add_f32_e32 v145, v145, v108
	v_exp_f32_e32 v111, v111
	v_add_f32_e32 v145, v145, v109
	v_cvt_pk_bf16_f32 v126, v108, v109
	v_add_f32_e32 v145, v145, v110
	v_add_f32_e32 v145, v145, v111
	v_cvt_pk_bf16_f32 v127, v110, v111
	s_waitcnt lgkmcnt(2)
; __device__ __forceinline__ void attn_pass_A2(const int tid, unsigned char* smem, const bf16_t* Q0w, int qpitch, const bf16_t* Kb, int kpitch, const bf16_t* Vb, int vpitch,
;                                              int b, int ntiles, float kmax, f32x16 (&o)[2][2], float (&linv)[2]) {
;     ...
;     for (int kt = 0; kt < ntiles; ++kt) {
;         if (kt + 1 < ntiles) gload(kt + 1);
;         const unsigned char* Ks = smem + (kt & 1) * BUF; const unsigned char* Vs = Ks + KBYTES;
;         const unsigned char* kp = Ks + r32 * KP + hi * 16;
;         const unsigned char* vp = Vs + (4 * hi + q4) * VP + (16 * nhalf + 4 * p4) * 2;
; #pragma unroll
;         for (int kb = 0; kb < 2; ++kb) {
;             bf16x8 pf[2][2];
;             {
;                 f32x16 s0, s1;
; #pragma unroll
;                 for (int r = 0; r < 16; ++r) { s0[r] = nshift[0]; s1[r] = nshift[1]; }
; #pragma unroll
;                 for (int ds = 0; ds < 4; ++ds) {
;                     const bf16x8 kf = *(const bf16x8*)(kp + kb * 32 * KP + ds * 32);
;                     const bf16x8 q0 = *(const bf16x8*)(qs + ds * 32), q1 = *(const bf16x8*)(qs + 32 * KP + ds * 32);
;                     s0 = __builtin_amdgcn_mfma_f32_32x32x16_bf16(kf, q0, s0, 0, 0, 0);
;                     s1 = __builtin_amdgcn_mfma_f32_32x32x16_bf16(kf, q1, s1, 0, 0, 0);
;                 }
;                 float l0 = 0.f, l1 = 0.f;
; #pragma unroll
;                 for (int r = 0; r < 16; ++r) { s0[r] = __builtin_amdgcn_exp2f(s0[r]); l0 += s0[r]; }
; #pragma unroll
;                 for (int r = 0; r < 16; ++r) { s1[r] = __builtin_amdgcn_exp2f(s1[r]); l1 += s1[r]; }
;                 lsum[0] += l0; lsum[1] += l1;
; #pragma unroll
;                 for (int j = 0; j < 2; ++j) {
;                     u32x4 w0, w1;
;                     w0.x = cvt_pk_bf16(s0[8 * j + 0], s0[8 * j + 1]); w0.y = cvt_pk_bf16(s0[8 * j + 2], s0[8 * j + 3]); w0.z = cvt_pk_bf16(s0[8 * j + 4], s0[8 * j + 5]); w0.w = cvt_pk_bf16(s0[8 * j + 6], s0[8 * j + 7]);
;                     w1.x = cvt_pk_bf16(s1[8 * j + 0], s1[8 * j + 1]); w1.y = cvt_pk_bf16(s1[8 * j + 2], s1[8 * j + 3]); w1.z = cvt_pk_bf16(s1[8 * j + 4], s1[8 * j + 5]); w1.w = cvt_pk_bf16(s1[8 * j + 6], s1[8 * j + 7]);
;                     pf[0][j] = __builtin_bit_cast(bf16x8, w0); pf[1][j] = __builtin_bit_cast(bf16x8, w1);
;                 }
;             }
	v_mfma_f32_32x32x16_bf16 v[48:63], v[218:221], v[116:119], v[48:63]
	v_mfma_f32_32x32x16_bf16 v[96:111], v[198:201], v[176:179], v[16:31]
	ds_read_b128 v[198:201], v222 offset:0
	v_exp_f32_e32 v80, v80
	v_exp_f32_e32 v81, v81
	v_exp_f32_e32 v82, v82
	v_add_f32_e32 v144, v144, v80
	v_exp_f32_e32 v83, v83
	v_mfma_f32_32x32x16_bf16 v[96:111], v[202:205], v[180:183], v[96:111]
	ds_read_b128 v[202:205], v222 offset:32
	s_add_i32 s71, s25, -1
	s_add_i32 s70, s59, 3
	s_min_u32 s70, s70, s71
	s_cmp_lt_u32 s70, 4
	s_cselect_b32 s2, s65, s32
	s_lshl_b32 s3, s70, 6
	s_add_i32 s2, s2, s3
	s_lshl_b32 s2, s2, 8
	s_add_u32 s60, s66, s2
	s_addc_u32 s61, s67, 0
	s_add_u32 s62, s68, s2
	s_addc_u32 s63, s69, 0
	v_add_f32_e32 v144, v144, v81
	v_cvt_pk_bf16_f32 v112, v80, v81
	v_exp_f32_e32 v84, v84
	v_add_f32_e32 v144, v144, v82
	v_exp_f32_e32 v85, v85
	v_mfma_f32_32x32x16_bf16 v[96:111], v[206:209], v[184:187], v[96:111]
	ds_read_b128 v[206:209], v222 offset:64
	v_add_f32_e32 v144, v144, v83
	v_cvt_pk_bf16_f32 v113, v82, v83
	v_exp_f32_e32 v86, v86
	v_add_f32_e32 v144, v144, v84
	v_exp_f32_e32 v87, v87
	v_add_f32_e32 v144, v144, v85
	v_mfma_f32_32x32x16_bf16 v[96:111], v[128:131], v[188:191], v[96:111]
	ds_read_b128 v[128:131], v222 offset:96
	global_load_dwordx4 v[132:135], v236, s[60:61]
	global_load_dwordx4 v[230:233], v236, s[62:63]
	v_cvt_pk_bf16_f32 v114, v84, v85
	v_exp_f32_e32 v88, v88
	v_add_f32_e32 v144, v144, v86
	v_exp_f32_e32 v89, v89
	v_add_f32_e32 v144, v144, v87
	v_cvt_pk_bf16_f32 v115, v86, v87
	v_mfma_f32_32x32x16_bf16 v[32:47], v[162:165], v[120:123], v[32:47]
	ds_read_b64_tr_b16 v[162:163], v223 offset:15360
	ds_read_b64_tr_b16 v[164:165], v223 offset:16896
	v_exp_f32_e32 v90, v90
	v_add_f32_e32 v144, v144, v88
	v_exp_f32_e32 v91, v91
	v_add_f32_e32 v144, v144, v89
	v_cvt_pk_bf16_f32 v116, v88, v89
	v_exp_f32_e32 v92, v92
	v_mfma_f32_32x32x16_bf16 v[0:15], v[166:169], v[120:123], v[0:15]
	ds_read_b64_tr_b16 v[166:167], v223 offset:15424
	ds_read_b64_tr_b16 v[168:169], v223 offset:16960
	v_add_f32_e32 v144, v144, v90
	v_exp_f32_e32 v93, v93
	v_add_f32_e32 v144, v144, v91
	v_cvt_pk_bf16_f32 v117, v90, v91
	v_exp_f32_e32 v94, v94
	v_mfma_f32_32x32x16_bf16 v[32:47], v[214:217], v[124:127], v[32:47]
	ds_read_b64_tr_b16 v[214:215], v223 offset:18432
	ds_read_b64_tr_b16 v[216:217], v223 offset:19968
	v_add_f32_e32 v144, v144, v92
	v_exp_f32_e32 v95, v95
	v_add_f32_e32 v144, v144, v93
	v_cvt_pk_bf16_f32 v118, v92, v93
	v_add_f32_e32 v144, v144, v94
	v_add_f32_e32 v144, v144, v95
	v_cvt_pk_bf16_f32 v119, v94, v95
	v_mfma_f32_32x32x16_bf16 v[0:15], v[218:221], v[124:127], v[0:15]
	ds_read_b64_tr_b16 v[218:219], v223 offset:18496
	ds_read_b64_tr_b16 v[220:221], v223 offset:20032
	s_waitcnt lgkmcnt(11)
	v_mfma_f32_32x32x16_bf16 v[80:95], v[198:201], v[146:149], v[16:31]
	v_exp_f32_e32 v96, v96
	v_exp_f32_e32 v97, v97
	v_exp_f32_e32 v98, v98
	v_add_f32_e32 v145, v145, v96
	v_exp_f32_e32 v99, v99
	s_waitcnt lgkmcnt(10)
	v_mfma_f32_32x32x16_bf16 v[80:95], v[202:205], v[150:153], v[80:95]
	v_add_f32_e32 v145, v145, v97
	v_cvt_pk_bf16_f32 v120, v96, v97
	v_exp_f32_e32 v100, v100
	v_add_f32_e32 v145, v145, v98
	v_exp_f32_e32 v101, v101
	s_waitcnt lgkmcnt(9)
	v_mfma_f32_32x32x16_bf16 v[80:95], v[206:209], v[154:157], v[80:95]
	v_add_f32_e32 v145, v145, v99
	v_cvt_pk_bf16_f32 v121, v98, v99
	v_exp_f32_e32 v102, v102
	v_add_f32_e32 v145, v145, v100
	v_exp_f32_e32 v103, v103
	v_add_f32_e32 v145, v145, v101
	s_waitcnt lgkmcnt(8)
	v_mfma_f32_32x32x16_bf16 v[80:95], v[128:131], v[158:161], v[80:95]
	v_cvt_pk_bf16_f32 v122, v100, v101
	v_exp_f32_e32 v104, v104
	v_add_f32_e32 v145, v145, v102
	v_exp_f32_e32 v105, v105
	v_add_f32_e32 v145, v145, v103
	v_cvt_pk_bf16_f32 v123, v102, v103
	s_waitcnt lgkmcnt(6)
	v_mfma_f32_32x32x16_bf16 v[64:79], v[162:165], v[112:115], v[64:79]
	v_exp_f32_e32 v106, v106
	v_add_f32_e32 v145, v145, v104
	v_exp_f32_e32 v107, v107
	v_add_f32_e32 v145, v145, v105
	v_cvt_pk_bf16_f32 v124, v104, v105
	v_exp_f32_e32 v108, v108
	s_waitcnt lgkmcnt(4)
	v_mfma_f32_32x32x16_bf16 v[48:63], v[166:169], v[112:115], v[48:63]
	v_add_f32_e32 v145, v145, v106
	v_exp_f32_e32 v109, v109
	v_add_f32_e32 v145, v145, v107
	v_cvt_pk_bf16_f32 v125, v106, v107
	v_exp_f32_e32 v110, v110
	s_waitcnt lgkmcnt(2)
	v_mfma_f32_32x32x16_bf16 v[64:79], v[214:217], v[116:119], v[64:79]
	v_add_f32_e32 v145, v145, v108
	v_exp_f32_e32 v111, v111
	v_add_f32_e32 v145, v145, v109
	v_cvt_pk_bf16_f32 v126, v108, v109
	v_add_f32_e32 v145, v145, v110
	v_add_f32_e32 v145, v145, v111
	v_cvt_pk_bf16_f32 v127, v110, v111
	s_waitcnt lgkmcnt(0)
; __device__ __forceinline__ void attn_pass_A2(const int tid, unsigned char* smem, const bf16_t* Q0w, int qpitch, const bf16_t* Kb, int kpitch, const bf16_t* Vb, int vpitch,
;                                              int b, int ntiles, float kmax, f32x16 (&o)[2][2], float (&linv)[2]) {
;     ...
;     for (int kt = 0; kt < ntiles; ++kt) {
;         if (kt + 1 < ntiles) gload(kt + 1);
;         const unsigned char* Ks = smem + (kt & 1) * BUF; const unsigned char* Vs = Ks + KBYTES;
;         const unsigned char* kp = Ks + r32 * KP + hi * 16;
;         const unsigned char* vp = Vs + (4 * hi + q4) * VP + (16 * nhalf + 4 * p4) * 2;
; #pragma unroll
;         for (int kb = 0; kb < 2; ++kb) {
;             bf16x8 pf[2][2];
;             {
;                 f32x16 s0, s1;
; #pragma unroll
;                 for (int r = 0; r < 16; ++r) { s0[r] = nshift[0]; s1[r] = nshift[1]; }
; #pragma unroll
;                 for (int ds = 0; ds < 4; ++ds) {
;                     const bf16x8 kf = *(const bf16x8*)(kp + kb * 32 * KP + ds * 32);
;                     const bf16x8 q0 = *(const bf16x8*)(qs + ds * 32), q1 = *(const bf16x8*)(qs + 32 * KP + ds * 32);
;                     s0 = __builtin_amdgcn_mfma_f32_32x32x16_bf16(kf, q0, s0, 0, 0, 0);
;                     s1 = __builtin_amdgcn_mfma_f32_32x32x16_bf16(kf, q1, s1, 0, 0, 0);
;                 }
;                 float l0 = 0.f, l1 = 0.f;
; #pragma unroll
;                 for (int r = 0; r < 16; ++r) { s0[r] = __builtin_amdgcn_exp2f(s0[r]); l0 += s0[r]; }
; #pragma unroll
;                 for (int r = 0; r < 16; ++r) { s1[r] = __builtin_amdgcn_exp2f(s1[r]); l1 += s1[r]; }
;                 lsum[0] += l0; lsum[1] += l1;
; #pragma unroll
;                 for (int j = 0; j < 2; ++j) {
;                     u32x4 w0, w1;
;                     w0.x = cvt_pk_bf16(s0[8 * j + 0], s0[8 * j + 1]); w0.y = cvt_pk_bf16(s0[8 * j + 2], s0[8 * j + 3]); w0.z = cvt_pk_bf16(s0[8 * j + 4], s0[8 * j + 5]); w0.w = cvt_pk_bf16(s0[8 * j + 6], s0[8 * j + 7]);
;                     w1.x = cvt_pk_bf16(s1[8 * j + 0], s1[8 * j + 1]); w1.y = cvt_pk_bf16(s1[8 * j + 2], s1[8 * j + 3]); w1.z = cvt_pk_bf16(s1[8 * j + 4], s1[8 * j + 5]); w1.w = cvt_pk_bf16(s1[8 * j + 6], s1[8 * j + 7]);
;                     pf[0][j] = __builtin_bit_cast(bf16x8, w0); pf[1][j] = __builtin_bit_cast(bf16x8, w1);
;                 }
;             }
	v_mfma_f32_32x32x16_bf16 v[48:63], v[218:221], v[116:119], v[48:63]
	v_mfma_f32_32x32x16_bf16 v[96:111], v[198:201], v[176:179], v[16:31]
	ds_read_b128 v[198:201], v222 offset:4608
	v_exp_f32_e32 v80, v80
	v_exp_f32_e32 v81, v81
	v_exp_f32_e32 v82, v82
	v_add_f32_e32 v144, v144, v80
	v_exp_f32_e32 v83, v83
	v_mfma_f32_32x32x16_bf16 v[96:111], v[202:205], v[180:183], v[96:111]
	ds_read_b128 v[202:205], v222 offset:4640
	v_add3_u32 v170, s58, v213, v138
	v_add3_u32 v171, s57, v173, v174
	v_add3_u32 v210, s58, v173, v174
	v_add_f32_e32 v144, v144, v81
	v_cvt_pk_bf16_f32 v112, v80, v81
	v_exp_f32_e32 v84, v84
	v_add_f32_e32 v144, v144, v82
	v_exp_f32_e32 v85, v85
	v_mfma_f32_32x32x16_bf16 v[96:111], v[206:209], v[184:187], v[96:111]
	ds_read_b128 v[206:209], v222 offset:4672
	v_add_f32_e32 v144, v144, v83
	v_cvt_pk_bf16_f32 v113, v82, v83
	v_exp_f32_e32 v86, v86
	v_add_f32_e32 v144, v144, v84
	v_exp_f32_e32 v87, v87
	v_add_f32_e32 v144, v144, v85
	v_mfma_f32_32x32x16_bf16 v[96:111], v[128:131], v[188:191], v[96:111]
	ds_read_b128 v[128:131], v222 offset:4704
	v_cvt_pk_bf16_f32 v114, v84, v85
	v_exp_f32_e32 v88, v88
	v_add_f32_e32 v144, v144, v86
	v_exp_f32_e32 v89, v89
	v_add_f32_e32 v144, v144, v87
	v_cvt_pk_bf16_f32 v115, v86, v87
	v_mfma_f32_32x32x16_bf16 v[32:47], v[162:165], v[120:123], v[32:47]
	ds_read_b64_tr_b16 v[162:163], v224 offset:9216
	ds_read_b64_tr_b16 v[164:165], v224 offset:10752
	v_exp_f32_e32 v90, v90
	v_add_f32_e32 v144, v144, v88
	v_exp_f32_e32 v91, v91
	v_add_f32_e32 v144, v144, v89
	v_cvt_pk_bf16_f32 v116, v88, v89
	v_exp_f32_e32 v92, v92
	v_mfma_f32_32x32x16_bf16 v[0:15], v[166:169], v[120:123], v[0:15]
	ds_read_b64_tr_b16 v[166:167], v224 offset:9280
	ds_read_b64_tr_b16 v[168:169], v224 offset:10816
	s_mov_b32 s2, s56
	s_mov_b32 s56, s57
	s_mov_b32 s57, s58
	s_mov_b32 s58, s2
	s_add_i32 s59, s59, 1
	v_add_f32_e32 v144, v144, v90
	v_exp_f32_e32 v93, v93
	v_add_f32_e32 v144, v144, v91
	v_cvt_pk_bf16_f32 v117, v90, v91
	v_exp_f32_e32 v94, v94
	v_mfma_f32_32x32x16_bf16 v[32:47], v[214:217], v[124:127], v[32:47]
	ds_read_b64_tr_b16 v[214:215], v224 offset:12288
	ds_read_b64_tr_b16 v[216:217], v224 offset:13824
	v_add_f32_e32 v144, v144, v92
	v_exp_f32_e32 v95, v95
	v_add_f32_e32 v144, v144, v93
	v_cvt_pk_bf16_f32 v118, v92, v93
	v_add_f32_e32 v144, v144, v94
	v_add_f32_e32 v144, v144, v95
	v_cvt_pk_bf16_f32 v119, v94, v95
	v_mfma_f32_32x32x16_bf16 v[0:15], v[218:221], v[124:127], v[0:15]
	ds_read_b64_tr_b16 v[218:219], v224 offset:12352
	ds_read_b64_tr_b16 v[220:221], v224 offset:13888
	s_add_i32 s71, s25, -2
	s_cmp_lt_u32 s59, s71
	s_waitcnt lgkmcnt(8)
	s_barrier
	s_cbranch_scc1 .Laattn_loop
	v_mfma_f32_32x32x16_bf16 v[80:95], v[198:201], v[146:149], v[16:31]
	v_exp_f32_e32 v96, v96
	v_exp_f32_e32 v97, v97
	v_exp_f32_e32 v98, v98
	v_add_f32_e32 v145, v145, v96
	v_exp_f32_e32 v99, v99
	v_mfma_f32_32x32x16_bf16 v[80:95], v[202:205], v[150:153], v[80:95]
	v_add_f32_e32 v145, v145, v97
	v_cvt_pk_bf16_f32 v120, v96, v97
	v_exp_f32_e32 v100, v100
	v_add_f32_e32 v145, v145, v98
	v_exp_f32_e32 v101, v101
	v_mfma_f32_32x32x16_bf16 v[80:95], v[206:209], v[154:157], v[80:95]
	v_add_f32_e32 v145, v145, v99
	v_cvt_pk_bf16_f32 v121, v98, v99
	v_exp_f32_e32 v102, v102
	v_add_f32_e32 v145, v145, v100
	v_exp_f32_e32 v103, v103
	v_add_f32_e32 v145, v145, v101
	v_mfma_f32_32x32x16_bf16 v[80:95], v[128:131], v[158:161], v[80:95]
	v_cvt_pk_bf16_f32 v122, v100, v101
	v_exp_f32_e32 v104, v104
	v_add_f32_e32 v145, v145, v102
	v_exp_f32_e32 v105, v105
	v_add_f32_e32 v145, v145, v103
	v_cvt_pk_bf16_f32 v123, v102, v103
	s_waitcnt lgkmcnt(6)
	v_mfma_f32_32x32x16_bf16 v[64:79], v[162:165], v[112:115], v[64:79]
	v_exp_f32_e32 v106, v106
	v_add_f32_e32 v145, v145, v104
	v_exp_f32_e32 v107, v107
	v_add_f32_e32 v145, v145, v105
	v_cvt_pk_bf16_f32 v124, v104, v105
	v_exp_f32_e32 v108, v108
	s_waitcnt lgkmcnt(4)
	v_mfma_f32_32x32x16_bf16 v[48:63], v[166:169], v[112:115], v[48:63]
	v_add_f32_e32 v145, v145, v106
	v_exp_f32_e32 v109, v109
	v_add_f32_e32 v145, v145, v107
	v_cvt_pk_bf16_f32 v125, v106, v107
	v_exp_f32_e32 v110, v110
	s_waitcnt lgkmcnt(2)
	v_mfma_f32_32x32x16_bf16 v[64:79], v[214:217], v[116:119], v[64:79]
	v_add_f32_e32 v145, v145, v108
	v_exp_f32_e32 v111, v111
	v_add_f32_e32 v145, v145, v109
	v_cvt_pk_bf16_f32 v126, v108, v109
	v_add_f32_e32 v145, v145, v110
	v_add_f32_e32 v145, v145, v111
	v_cvt_pk_bf16_f32 v127, v110, v111
	s_waitcnt lgkmcnt(0)
	v_mfma_f32_32x32x16_bf16 v[48:63], v[218:221], v[116:119], v[48:63]
	v_mfma_f32_32x32x16_bf16 v[96:111], v[198:201], v[176:179], v[16:31]
	ds_read_b128 v[198:201], v170 offset:0
	v_exp_f32_e32 v80, v80
	v_exp_f32_e32 v81, v81
	v_exp_f32_e32 v82, v82
	v_add_f32_e32 v144, v144, v80
	v_exp_f32_e32 v83, v83
	v_mfma_f32_32x32x16_bf16 v[96:111], v[202:205], v[180:183], v[96:111]
	ds_read_b128 v[202:205], v170 offset:32
	v_add_f32_e32 v144, v144, v81
	v_cvt_pk_bf16_f32 v112, v80, v81
	v_exp_f32_e32 v84, v84
	v_add_f32_e32 v144, v144, v82
	v_exp_f32_e32 v85, v85
	v_mfma_f32_32x32x16_bf16 v[96:111], v[206:209], v[184:187], v[96:111]
	ds_read_b128 v[206:209], v170 offset:64
	v_add_f32_e32 v144, v144, v83
	v_cvt_pk_bf16_f32 v113, v82, v83
	v_exp_f32_e32 v86, v86
	v_add_f32_e32 v144, v144, v84
	v_exp_f32_e32 v87, v87
	v_add_f32_e32 v144, v144, v85
	v_mfma_f32_32x32x16_bf16 v[96:111], v[128:131], v[188:191], v[96:111]
	ds_read_b128 v[128:131], v170 offset:96
	v_cvt_pk_bf16_f32 v114, v84, v85
	v_exp_f32_e32 v88, v88
	v_add_f32_e32 v144, v144, v86
	v_exp_f32_e32 v89, v89
	v_add_f32_e32 v144, v144, v87
	v_cvt_pk_bf16_f32 v115, v86, v87
	v_mfma_f32_32x32x16_bf16 v[32:47], v[162:165], v[120:123], v[32:47]
	ds_read_b64_tr_b16 v[162:163], v171 offset:15360
	ds_read_b64_tr_b16 v[164:165], v171 offset:16896
	v_exp_f32_e32 v90, v90
	v_add_f32_e32 v144, v144, v88
	v_exp_f32_e32 v91, v91
	v_add_f32_e32 v144, v144, v89
	v_cvt_pk_bf16_f32 v116, v88, v89
	v_exp_f32_e32 v92, v92
	v_mfma_f32_32x32x16_bf16 v[0:15], v[166:169], v[120:123], v[0:15]
	ds_read_b64_tr_b16 v[166:167], v171 offset:15424
	ds_read_b64_tr_b16 v[168:169], v171 offset:16960
	v_add_f32_e32 v144, v144, v90
	v_exp_f32_e32 v93, v93
	v_add_f32_e32 v144, v144, v91
	v_cvt_pk_bf16_f32 v117, v90, v91
	v_exp_f32_e32 v94, v94
	v_mfma_f32_32x32x16_bf16 v[32:47], v[214:217], v[124:127], v[32:47]
	ds_read_b64_tr_b16 v[214:215], v171 offset:18432
	ds_read_b64_tr_b16 v[216:217], v171 offset:19968
	v_add_f32_e32 v144, v144, v92
	v_exp_f32_e32 v95, v95
	v_add_f32_e32 v144, v144, v93
	v_cvt_pk_bf16_f32 v118, v92, v93
	v_add_f32_e32 v144, v144, v94
	v_add_f32_e32 v144, v144, v95
	v_cvt_pk_bf16_f32 v119, v94, v95
	v_mfma_f32_32x32x16_bf16 v[0:15], v[218:221], v[124:127], v[0:15]
	ds_read_b64_tr_b16 v[218:219], v171 offset:18496
	ds_read_b64_tr_b16 v[220:221], v171 offset:20032
	s_waitcnt lgkmcnt(11)
; __device__ __forceinline__ void attn_pass_A2(const int tid, unsigned char* smem, const bf16_t* Q0w, int qpitch, const bf16_t* Kb, int kpitch, const bf16_t* Vb, int vpitch,
;                                              int b, int ntiles, float kmax, f32x16 (&o)[2][2], float (&linv)[2]) {
;     ...
;     for (int kt = 0; kt < ntiles; ++kt) {
;         if (kt + 1 < ntiles) gload(kt + 1);
;         const unsigned char* Ks = smem + (kt & 1) * BUF; const unsigned char* Vs = Ks + KBYTES;
;         const unsigned char* kp = Ks + r32 * KP + hi * 16;
;         const unsigned char* vp = Vs + (4 * hi + q4) * VP + (16 * nhalf + 4 * p4) * 2;
; #pragma unroll
;         for (int kb = 0; kb < 2; ++kb) {
;             bf16x8 pf[2][2];
;             {
;                 f32x16 s0, s1;
; #pragma unroll
;                 for (int r = 0; r < 16; ++r) { s0[r] = nshift[0]; s1[r] = nshift[1]; }
; #pragma unroll
;                 for (int ds = 0; ds < 4; ++ds) {
;                     const bf16x8 kf = *(const bf16x8*)(kp + kb * 32 * KP + ds * 32);
;                     const bf16x8 q0 = *(const bf16x8*)(qs + ds * 32), q1 = *(const bf16x8*)(qs + 32 * KP + ds * 32);
;                     s0 = __builtin_amdgcn_mfma_f32_32x32x16_bf16(kf, q0, s0, 0, 0, 0);
;                     s1 = __builtin_amdgcn_mfma_f32_32x32x16_bf16(kf, q1, s1, 0, 0, 0);
;                 }
;                 float l0 = 0.f, l1 = 0.f;
; #pragma unroll
;                 for (int r = 0; r < 16; ++r) { s0[r] = __builtin_amdgcn_exp2f(s0[r]); l0 += s0[r]; }
; #pragma unroll
;                 for (int r = 0; r < 16; ++r) { s1[r] = __builtin_amdgcn_exp2f(s1[r]); l1 += s1[r]; }
;                 lsum[0] += l0; lsum[1] += l1;
; #pragma unroll
;                 for (int j = 0; j < 2; ++j) {
;                     u32x4 w0, w1;
;                     w0.x = cvt_pk_bf16(s0[8 * j + 0], s0[8 * j + 1]); w0.y = cvt_pk_bf16(s0[8 * j + 2], s0[8 * j + 3]); w0.z = cvt_pk_bf16(s0[8 * j + 4], s0[8 * j + 5]); w0.w = cvt_pk_bf16(s0[8 * j + 6], s0[8 * j + 7]);
;                     w1.x = cvt_pk_bf16(s1[8 * j + 0], s1[8 * j + 1]); w1.y = cvt_pk_bf16(s1[8 * j + 2], s1[8 * j + 3]); w1.z = cvt_pk_bf16(s1[8 * j + 4], s1[8 * j + 5]); w1.w = cvt_pk_bf16(s1[8 * j + 6], s1[8 * j + 7]);
;                     pf[0][j] = __builtin_bit_cast(bf16x8, w0); pf[1][j] = __builtin_bit_cast(bf16x8, w1);
;                 }
;             }
	v_mfma_f32_32x32x16_bf16 v[80:95], v[198:201], v[146:149], v[16:31]
	v_exp_f32_e32 v96, v96
	v_exp_f32_e32 v97, v97
	v_exp_f32_e32 v98, v98
	v_add_f32_e32 v145, v145, v96
	v_exp_f32_e32 v99, v99
	s_waitcnt lgkmcnt(10)
	v_mfma_f32_32x32x16_bf16 v[80:95], v[202:205], v[150:153], v[80:95]
	v_add_f32_e32 v145, v145, v97
	v_cvt_pk_bf16_f32 v120, v96, v97
	v_exp_f32_e32 v100, v100
	v_add_f32_e32 v145, v145, v98
	v_exp_f32_e32 v101, v101
	s_waitcnt lgkmcnt(9)
	v_mfma_f32_32x32x16_bf16 v[80:95], v[206:209], v[154:157], v[80:95]
	v_add_f32_e32 v145, v145, v99
	v_cvt_pk_bf16_f32 v121, v98, v99
	v_exp_f32_e32 v102, v102
	v_add_f32_e32 v145, v145, v100
	v_exp_f32_e32 v103, v103
	v_add_f32_e32 v145, v145, v101
	s_waitcnt lgkmcnt(8)
	v_mfma_f32_32x32x16_bf16 v[80:95], v[128:131], v[158:161], v[80:95]
	v_cvt_pk_bf16_f32 v122, v100, v101
	v_exp_f32_e32 v104, v104
	v_add_f32_e32 v145, v145, v102
	v_exp_f32_e32 v105, v105
	v_add_f32_e32 v145, v145, v103
	v_cvt_pk_bf16_f32 v123, v102, v103
	s_waitcnt lgkmcnt(6)
	v_mfma_f32_32x32x16_bf16 v[64:79], v[162:165], v[112:115], v[64:79]
	v_exp_f32_e32 v106, v106
	v_add_f32_e32 v145, v145, v104
	v_exp_f32_e32 v107, v107
	v_add_f32_e32 v145, v145, v105
	v_cvt_pk_bf16_f32 v124, v104, v105
	v_exp_f32_e32 v108, v108
	s_waitcnt lgkmcnt(4)
	v_mfma_f32_32x32x16_bf16 v[48:63], v[166:169], v[112:115], v[48:63]
	v_add_f32_e32 v145, v145, v106
	v_exp_f32_e32 v109, v109
	v_add_f32_e32 v145, v145, v107
	v_cvt_pk_bf16_f32 v125, v106, v107
	v_exp_f32_e32 v110, v110
	s_waitcnt lgkmcnt(2)
	v_mfma_f32_32x32x16_bf16 v[64:79], v[214:217], v[116:119], v[64:79]
	v_add_f32_e32 v145, v145, v108
	v_exp_f32_e32 v111, v111
	v_add_f32_e32 v145, v145, v109
	v_cvt_pk_bf16_f32 v126, v108, v109
	v_add_f32_e32 v145, v145, v110
	v_add_f32_e32 v145, v145, v111
	v_cvt_pk_bf16_f32 v127, v110, v111
	s_waitcnt lgkmcnt(0)
	v_mfma_f32_32x32x16_bf16 v[48:63], v[218:221], v[116:119], v[48:63]
	v_mfma_f32_32x32x16_bf16 v[96:111], v[198:201], v[176:179], v[16:31]
	ds_read_b128 v[198:201], v170 offset:4608
	v_exp_f32_e32 v80, v80
	v_exp_f32_e32 v81, v81
	v_exp_f32_e32 v82, v82
	v_add_f32_e32 v144, v144, v80
	v_exp_f32_e32 v83, v83
	v_mfma_f32_32x32x16_bf16 v[96:111], v[202:205], v[180:183], v[96:111]
	ds_read_b128 v[202:205], v170 offset:4640
	v_add3_u32 v222, s58, v213, v138
	v_add3_u32 v223, s57, v173, v174
	v_add3_u32 v224, s58, v173, v174
	v_add_f32_e32 v144, v144, v81
	v_cvt_pk_bf16_f32 v112, v80, v81
	v_exp_f32_e32 v84, v84
	v_add_f32_e32 v144, v144, v82
	v_exp_f32_e32 v85, v85
	v_mfma_f32_32x32x16_bf16 v[96:111], v[206:209], v[184:187], v[96:111]
	ds_read_b128 v[206:209], v170 offset:4672
	v_add_f32_e32 v144, v144, v83
	v_cvt_pk_bf16_f32 v113, v82, v83
	v_exp_f32_e32 v86, v86
	v_add_f32_e32 v144, v144, v84
	v_exp_f32_e32 v87, v87
	v_add_f32_e32 v144, v144, v85
	v_mfma_f32_32x32x16_bf16 v[96:111], v[128:131], v[188:191], v[96:111]
	ds_read_b128 v[128:131], v170 offset:4704
	v_cvt_pk_bf16_f32 v114, v84, v85
	v_exp_f32_e32 v88, v88
	v_add_f32_e32 v144, v144, v86
	v_exp_f32_e32 v89, v89
	v_add_f32_e32 v144, v144, v87
	v_cvt_pk_bf16_f32 v115, v86, v87
	v_mfma_f32_32x32x16_bf16 v[32:47], v[162:165], v[120:123], v[32:47]
	ds_read_b64_tr_b16 v[162:163], v210 offset:9216
	ds_read_b64_tr_b16 v[164:165], v210 offset:10752
	v_exp_f32_e32 v90, v90
	v_add_f32_e32 v144, v144, v88
	v_exp_f32_e32 v91, v91
	v_add_f32_e32 v144, v144, v89
	v_cvt_pk_bf16_f32 v116, v88, v89
	v_exp_f32_e32 v92, v92
	v_mfma_f32_32x32x16_bf16 v[0:15], v[166:169], v[120:123], v[0:15]
	ds_read_b64_tr_b16 v[166:167], v210 offset:9280
	ds_read_b64_tr_b16 v[168:169], v210 offset:10816
	s_mov_b32 s2, s56
	s_mov_b32 s56, s57
	s_mov_b32 s57, s58
	s_mov_b32 s58, s2
	s_add_i32 s59, s59, 1
	v_add_f32_e32 v144, v144, v90
	v_exp_f32_e32 v93, v93
	v_add_f32_e32 v144, v144, v91
	v_cvt_pk_bf16_f32 v117, v90, v91
	v_exp_f32_e32 v94, v94
	v_mfma_f32_32x32x16_bf16 v[32:47], v[214:217], v[124:127], v[32:47]
	ds_read_b64_tr_b16 v[214:215], v210 offset:12288
	ds_read_b64_tr_b16 v[216:217], v210 offset:13824
	v_add_f32_e32 v144, v144, v92
	v_exp_f32_e32 v95, v95
	v_add_f32_e32 v144, v144, v93
	v_cvt_pk_bf16_f32 v118, v92, v93
	v_add_f32_e32 v144, v144, v94
	v_add_f32_e32 v144, v144, v95
	v_cvt_pk_bf16_f32 v119, v94, v95
	v_mfma_f32_32x32x16_bf16 v[0:15], v[218:221], v[124:127], v[0:15]
	ds_read_b64_tr_b16 v[218:219], v210 offset:12352
	ds_read_b64_tr_b16 v[220:221], v210 offset:13888
	s_waitcnt lgkmcnt(8)
	s_barrier
; __device__ __forceinline__ s16x4 ld_tr(const unsigned char* p) { return __builtin_bit_cast(s16x4, __builtin_amdgcn_ds_read_tr16_b64_v4i16((LAS s16x4*)p)); }
; __device__ __forceinline__ void attn_pass_A2(const int tid, unsigned char* smem, const bf16_t* Q0w, int qpitch, const bf16_t* Kb, int kpitch, const bf16_t* Vb, int vpitch,
;                                              int b, int ntiles, float kmax, f32x16 (&o)[2][2], float (&linv)[2]) {
;     ...
; #pragma unroll
;             for (int d0 = 0; d0 < 2; ++d0)
; #pragma unroll
;                 for (int j = 0; j < 2; ++j) {
;                     const unsigned char* a = vp + (32 * kb + 16 * j) * VP + d0 * 64;
;                     const s16x4 lo = ld_tr(a), h4 = ld_tr(a + 8 * VP);
;                     const bf16x8 vf = (bf16x8){lo[0], lo[1], lo[2], lo[3], h4[0], h4[1], h4[2], h4[3]};
;                     o[0][d0] = __builtin_amdgcn_mfma_f32_32x32x16_bf16(vf, pf[0][j], o[0][d0], 0, 0, 0);
;                     o[1][d0] = __builtin_amdgcn_mfma_f32_32x32x16_bf16(vf, pf[1][j], o[1][d0], 0, 0, 0);
;                 }
;             __builtin_amdgcn_sched_barrier(0);
;         }
;         if (kt + 1 < ntiles) lwrite((kt + 1) & 1);
;         __syncthreads();
;     }
	v_mfma_f32_32x32x16_bf16 v[80:95], v[198:201], v[146:149], v[16:31]
	v_exp_f32_e32 v96, v96
	v_exp_f32_e32 v97, v97
	v_exp_f32_e32 v98, v98
	v_add_f32_e32 v145, v145, v96
	v_exp_f32_e32 v99, v99
	v_mfma_f32_32x32x16_bf16 v[80:95], v[202:205], v[150:153], v[80:95]
	v_add_f32_e32 v145, v145, v97
	v_cvt_pk_bf16_f32 v120, v96, v97
	v_exp_f32_e32 v100, v100
	v_add_f32_e32 v145, v145, v98
	v_exp_f32_e32 v101, v101
	v_mfma_f32_32x32x16_bf16 v[80:95], v[206:209], v[154:157], v[80:95]
	v_add_f32_e32 v145, v145, v99
	v_cvt_pk_bf16_f32 v121, v98, v99
	v_exp_f32_e32 v102, v102
	v_add_f32_e32 v145, v145, v100
	v_exp_f32_e32 v103, v103
	v_add_f32_e32 v145, v145, v101
	v_mfma_f32_32x32x16_bf16 v[80:95], v[128:131], v[158:161], v[80:95]
	v_cvt_pk_bf16_f32 v122, v100, v101
	v_exp_f32_e32 v104, v104
	v_add_f32_e32 v145, v145, v102
	v_exp_f32_e32 v105, v105
	v_add_f32_e32 v145, v145, v103
	v_cvt_pk_bf16_f32 v123, v102, v103
	s_waitcnt lgkmcnt(6)
	v_mfma_f32_32x32x16_bf16 v[64:79], v[162:165], v[112:115], v[64:79]
	v_exp_f32_e32 v106, v106
	v_add_f32_e32 v145, v145, v104
	v_exp_f32_e32 v107, v107
	v_add_f32_e32 v145, v145, v105
	v_cvt_pk_bf16_f32 v124, v104, v105
	v_exp_f32_e32 v108, v108
	s_waitcnt lgkmcnt(4)
	v_mfma_f32_32x32x16_bf16 v[48:63], v[166:169], v[112:115], v[48:63]
	v_add_f32_e32 v145, v145, v106
	v_exp_f32_e32 v109, v109
	v_add_f32_e32 v145, v145, v107
	v_cvt_pk_bf16_f32 v125, v106, v107
	v_exp_f32_e32 v110, v110
	s_waitcnt lgkmcnt(2)
	v_mfma_f32_32x32x16_bf16 v[64:79], v[214:217], v[116:119], v[64:79]
	v_add_f32_e32 v145, v145, v108
	v_exp_f32_e32 v111, v111
	v_add_f32_e32 v145, v145, v109
	v_cvt_pk_bf16_f32 v126, v108, v109
	v_add_f32_e32 v145, v145, v110
	v_add_f32_e32 v145, v145, v111
	v_cvt_pk_bf16_f32 v127, v110, v111
	s_waitcnt lgkmcnt(0)
	v_mfma_f32_32x32x16_bf16 v[48:63], v[218:221], v[116:119], v[48:63]
	v_mfma_f32_32x32x16_bf16 v[96:111], v[198:201], v[176:179], v[16:31]
	v_exp_f32_e32 v80, v80
	v_exp_f32_e32 v81, v81
	v_exp_f32_e32 v82, v82
	v_add_f32_e32 v144, v144, v80
	v_exp_f32_e32 v83, v83
	v_mfma_f32_32x32x16_bf16 v[96:111], v[202:205], v[180:183], v[96:111]
	v_add_f32_e32 v144, v144, v81
	v_cvt_pk_bf16_f32 v112, v80, v81
	v_exp_f32_e32 v84, v84
	v_add_f32_e32 v144, v144, v82
	v_exp_f32_e32 v85, v85
	v_mfma_f32_32x32x16_bf16 v[96:111], v[206:209], v[184:187], v[96:111]
	v_add_f32_e32 v144, v144, v83
	v_cvt_pk_bf16_f32 v113, v82, v83
	v_exp_f32_e32 v86, v86
	v_add_f32_e32 v144, v144, v84
	v_exp_f32_e32 v87, v87
	v_add_f32_e32 v144, v144, v85
	v_mfma_f32_32x32x16_bf16 v[96:111], v[128:131], v[188:191], v[96:111]
	v_cvt_pk_bf16_f32 v114, v84, v85
	v_exp_f32_e32 v88, v88
	v_add_f32_e32 v144, v144, v86
	v_exp_f32_e32 v89, v89
	v_add_f32_e32 v144, v144, v87
	v_cvt_pk_bf16_f32 v115, v86, v87
	v_mfma_f32_32x32x16_bf16 v[32:47], v[162:165], v[120:123], v[32:47]
	ds_read_b64_tr_b16 v[162:163], v223 offset:15360
	ds_read_b64_tr_b16 v[164:165], v223 offset:16896
	v_exp_f32_e32 v90, v90
	v_add_f32_e32 v144, v144, v88
	v_exp_f32_e32 v91, v91
	v_add_f32_e32 v144, v144, v89
	v_cvt_pk_bf16_f32 v116, v88, v89
	v_exp_f32_e32 v92, v92
	v_mfma_f32_32x32x16_bf16 v[0:15], v[166:169], v[120:123], v[0:15]
	ds_read_b64_tr_b16 v[166:167], v223 offset:15424
	ds_read_b64_tr_b16 v[168:169], v223 offset:16960
	v_add_f32_e32 v144, v144, v90
	v_exp_f32_e32 v93, v93
	v_add_f32_e32 v144, v144, v91
	v_cvt_pk_bf16_f32 v117, v90, v91
	v_exp_f32_e32 v94, v94
	v_mfma_f32_32x32x16_bf16 v[32:47], v[214:217], v[124:127], v[32:47]
	ds_read_b64_tr_b16 v[214:215], v223 offset:18432
	ds_read_b64_tr_b16 v[216:217], v223 offset:19968
	v_add_f32_e32 v144, v144, v92
	v_exp_f32_e32 v95, v95
	v_add_f32_e32 v144, v144, v93
	v_cvt_pk_bf16_f32 v118, v92, v93
	v_add_f32_e32 v144, v144, v94
	v_add_f32_e32 v144, v144, v95
	v_cvt_pk_bf16_f32 v119, v94, v95
	v_mfma_f32_32x32x16_bf16 v[0:15], v[218:221], v[124:127], v[0:15]
	ds_read_b64_tr_b16 v[218:219], v223 offset:18496
	ds_read_b64_tr_b16 v[220:221], v223 offset:20032
	s_waitcnt lgkmcnt(6)
	v_mfma_f32_32x32x16_bf16 v[64:79], v[162:165], v[112:115], v[64:79]
	v_exp_f32_e32 v96, v96
	v_exp_f32_e32 v97, v97
	v_exp_f32_e32 v98, v98
	v_add_f32_e32 v145, v145, v96
	v_exp_f32_e32 v99, v99
	v_add_f32_e32 v145, v145, v97
	v_cvt_pk_bf16_f32 v120, v96, v97
	v_exp_f32_e32 v100, v100
	v_add_f32_e32 v145, v145, v98
	v_exp_f32_e32 v101, v101
	v_add_f32_e32 v145, v145, v99
	v_cvt_pk_bf16_f32 v121, v98, v99
	v_exp_f32_e32 v102, v102
	s_waitcnt lgkmcnt(4)
	v_mfma_f32_32x32x16_bf16 v[48:63], v[166:169], v[112:115], v[48:63]
	v_add_f32_e32 v145, v145, v100
	v_exp_f32_e32 v103, v103
	v_add_f32_e32 v145, v145, v101
	v_cvt_pk_bf16_f32 v122, v100, v101
	v_exp_f32_e32 v104, v104
	v_add_f32_e32 v145, v145, v102
	v_exp_f32_e32 v105, v105
	v_add_f32_e32 v145, v145, v103
	v_cvt_pk_bf16_f32 v123, v102, v103
	v_exp_f32_e32 v106, v106
	v_add_f32_e32 v145, v145, v104
	v_exp_f32_e32 v107, v107
	v_add_f32_e32 v145, v145, v105
	s_waitcnt lgkmcnt(2)
	v_mfma_f32_32x32x16_bf16 v[64:79], v[214:217], v[116:119], v[64:79]
	v_cvt_pk_bf16_f32 v124, v104, v105
	v_exp_f32_e32 v108, v108
	v_add_f32_e32 v145, v145, v106
	v_exp_f32_e32 v109, v109
	v_add_f32_e32 v145, v145, v107
	v_cvt_pk_bf16_f32 v125, v106, v107
	v_exp_f32_e32 v110, v110
	v_add_f32_e32 v145, v145, v108
	v_exp_f32_e32 v111, v111
	v_add_f32_e32 v145, v145, v109
	v_cvt_pk_bf16_f32 v126, v108, v109
	v_add_f32_e32 v145, v145, v110
	v_add_f32_e32 v145, v145, v111
	v_cvt_pk_bf16_f32 v127, v110, v111
	s_waitcnt lgkmcnt(0)
	v_mfma_f32_32x32x16_bf16 v[48:63], v[218:221], v[116:119], v[48:63]
	v_mfma_f32_32x32x16_bf16 v[32:47], v[162:165], v[120:123], v[32:47]
	v_mfma_f32_32x32x16_bf16 v[0:15], v[166:169], v[120:123], v[0:15]
	v_mfma_f32_32x32x16_bf16 v[32:47], v[214:217], v[124:127], v[32:47]
	v_mfma_f32_32x32x16_bf16 v[0:15], v[218:221], v[124:127], v[0:15]
	s_waitcnt lgkmcnt(0)
	s_barrier
	s_waitcnt vmcnt(0)
